# scan chunk boundary shortened: look-ahead load addresses carried with their constants, dead first-token path removed, strides and tree masks as per-unit SGPR constants
# speedup vs baseline: 1.0022x; 1.0016x over previous
; __device__ __forceinline__ void scan_load(const bf16_t* Z, const bf16_t* LO, size_t mrow0, int t0, int tid, int colb, u32x2 (&pz)[8]) {
;     const int t = t0 + (tid >> 4); const size_t m = mrow0 + t; const bf16_t* zr = Z + m * ZC + colb; const bf16_t* lo = LO + m * LOC + colb;
;     pz[0] = *(const u32x2*)(zr); pz[1] = *(const u32x2*)(zr + 512); pz[2] = *(const u32x2*)(zr + 1024);
;     if (t > 0) { pz[3] = *(const u32x2*)(zr - ZC); pz[4] = *(const u32x2*)(zr + 512 - ZC); pz[5] = *(const u32x2*)(zr + 1024 - ZC); } else { pz[3] = (u32x2){0u, 0u}; pz[4] = (u32x2){0u, 0u}; pz[5] = (u32x2){0u, 0u}; }
;     pz[6] = *(const u32x2*)(lo); pz[7] = *(const u32x2*)(lo + 512);
; }
; __device__ __forceinline__ void scan_phase(const KAS Args& a, LAS unsigned char* lds, int i, const int tid_, const int bid, const int nblk) {
;     ...
;         for (int c = 0; c < T / TC; ++c) {
;             const bool more = (c + 1 < T / TC);
;             if (more) scan_load(Z, LO, mrow0, (c + 1) * TC, tid, colb, pz);
;             const LAS float* buf = bufs + (c & 1) * (TC * SST); LAS float* yb = ybuf + (c & 1) * (TC * 32);
;             {
;                 const LAS float* sb = buf + 4 * cgp; const LAS float* vb = buf + 320 + rl;
;                 f32x4 kk4 = *(const LAS f32x4*)(sb), nb4 = *(const LAS f32x4*)(sb + 64), w4 = *(const LAS f32x4*)(sb + 128), k4 = *(const LAS f32x4*)(sb + 192), r4 = *(const LAS f32x4*)(sb + 256);
;                 float v = vb[0], ysel = 0.f;
; #pragma unroll
;                 for (int t = 0; t < TC; ++t) {
;                     f32x4 kk4n = kk4, nb4n = nb4, w4n = w4, k4n = k4, r4n = r4; float vn = v;
;                     if (t + 1 < TC) { const LAS float* sn = sb + (t + 1) * SST;
;                         kk4n = *(const LAS f32x4*)(sn); nb4n = *(const LAS f32x4*)(sn + 64); w4n = *(const LAS f32x4*)(sn + 128); k4n = *(const LAS f32x4*)(sn + 192); r4n = *(const LAS f32x4*)(sn + 256); vn = vb[(t + 1) * SST]; }
;                     __builtin_amdgcn_sched_barrier(0x6);
;                     float sa = fmaf(S[3], kk4[3], fmaf(S[2], kk4[2], fmaf(S[1], kk4[1], S[0] * kk4[0])));
;                     const f32x4 Tm = S * w4 + k4 * v;
;                     sa = row16_sum(sa);
;                     S = Tm + nb4 * sa;
;                     float y = fmaf(S[3], r4[3], fmaf(S[2], r4[2], fmaf(S[1], r4[1], S[0] * r4[0]))); y = row16_sum(y);
.Lscs_189:
	s_or_b64 exec, exec, s[16:17]
	v_lshl_add_u64 v[28:29], s[88:89], 0, v[102:103]
	v_add_co_u32_e32 v28, vcc, 0x31818000, v28
	s_nop 1
	v_addc_co_u32_e32 v29, vcc, 0, v29, vcc
	global_load_dwordx2 v[92:93], v[28:29], off
	global_load_dwordx2 v[94:95], v[28:29], off offset:1024
	s_mov_b64 s[2:3], 0x18000
	v_lshl_add_u64 v[102:103], v[102:103], 0, s[2:3]
	s_mov_b64 s[2:3], 0x2c000
	v_lshl_add_u64 v[104:105], v[104:105], 0, s[2:3]
	v_add_u32_e32 v121, 32, v121
	v_lshl_add_u64 v[104:105], s[88:89], 0, v[104:105]
	s_mov_b64 s[2:3], 0x1382c000
	v_lshl_add_u64 v[104:105], v[104:105], 0, s[2:3]
	v_lshl_add_u64 v[102:103], s[88:89], 0, v[102:103]
	s_mov_b64 s[2:3], 0x31818000
	v_lshl_add_u64 v[102:103], v[102:103], 0, s[2:3]
	s_mov_b64 s[16:17], 0x400
	s_mov_b64 s[18:19], 0x18000
	s_mov_b64 s[20:21], 0x2c000
	s_mov_b32 s22, 0xffffee00
	s_mov_b32 s23, -1
	s_mov_b32 s8, 0xaaaaaaaa
	s_mov_b32 s9, 0xaaaaaaaa
	s_mov_b32 s10, 0xcccccccc
	s_mov_b32 s11, 0xcccccccc
	s_mov_b32 s12, 0xf0f0f0f0
	s_mov_b32 s13, 0xf0f0f0f0
	s_mov_b32 s14, 0xff00ff00
	s_mov_b32 s15, 0xff00ff00
	s_waitcnt lgkmcnt(0)
	s_barrier
	s_branch .LBB0_184
.LBB0_182:
	s_or_b64 exec, exec, s[2:3]
	s_cmpk_ge_i32 s67, 0x7e
	s_cbranch_scc1 .LBB0_183
	global_load_dwordx2 v[80:81], v[104:105], off
	global_load_dwordx2 v[82:83], v[104:105], off offset:1024
	global_load_dwordx2 v[84:85], v[104:105], off offset:2048
	v_lshl_add_u64 v[28:29], v[104:105], 0, s[22:23]
	global_load_dwordx2 v[86:87], v[28:29], off offset:-1024
	global_load_dwordx2 v[88:89], v[28:29], off
	global_load_dwordx2 v[90:91], v[28:29], off offset:1024
	global_load_dwordx2 v[92:93], v[102:103], off
	global_load_dwordx2 v[94:95], v[102:103], off offset:1024
.LBB0_183:
	v_lshl_add_u32 v2, v186, 2, s63
	s_waitcnt lgkmcnt(0)
	s_barrier
	ds_read2st64_b32 v[28:29], v2 offset1:8
	v_lshl_add_u64 v[100:101], v[100:101], 0, s[16:17]
	v_lshl_add_u64 v[30:31], v[98:99], 0, v[68:69]
	v_lshl_add_u64 v[102:103], v[102:103], 0, s[18:19]
	v_lshl_add_u64 v[104:105], v[104:105], 0, s[20:21]
	s_waitcnt lgkmcnt(0)
	v_cvt_pk_bf16_f32 v2, v28, s0
	global_store_short v[30:31], v2, off
	v_cvt_pk_bf16_f32 v2, v29, s0
	v_lshl_add_u64 v[28:29], v[96:97], 0, v[68:69]
	v_lshl_add_u64 v[96:97], v[96:97], 0, s[98:99]
	v_lshl_add_u64 v[98:99], v[98:99], 0, s[98:99]
	s_cmpk_eq_i32 s62, 0x80
	s_mov_b32 s67, s62
	global_store_short v[28:29], v2, off
	s_cbranch_scc1 .LBB0_172

; #define LAS __attribute__((address_space(3)))
; __device__ __forceinline__ float row16_sum(float x) { x += dpp_mov<0xB1>(x); x += dpp_mov<0x4E>(x); x += dpp_mov<0x124>(x); x += dpp_mov<0x128>(x); return x; }
; __device__ __forceinline__ void scan_phase(const KAS Args& a, LAS unsigned char* lds, int i, const int tid_, const int bid, const int nblk) {
;     ...
;         for (int c = 0; c < T / TC; ++c) {
;             const bool more = (c + 1 < T / TC);
;             if (more) scan_load(Z, LO, mrow0, (c + 1) * TC, tid, colb, pz);
;             const LAS float* buf = bufs + (c & 1) * (TC * SST); LAS float* yb = ybuf + (c & 1) * (TC * 32);
;             {
;                 const LAS float* sb = buf + 4 * cgp; const LAS float* vb = buf + 320 + rl;
;                 f32x4 kk4 = *(const LAS f32x4*)(sb), nb4 = *(const LAS f32x4*)(sb + 64), w4 = *(const LAS f32x4*)(sb + 128), k4 = *(const LAS f32x4*)(sb + 192), r4 = *(const LAS f32x4*)(sb + 256);
;                 float v = vb[0], ysel = 0.f;
; #pragma unroll
;                 for (int t = 0; t < TC; ++t) {
;                     f32x4 kk4n = kk4, nb4n = nb4, w4n = w4, k4n = k4, r4n = r4; float vn = v;
;                     if (t + 1 < TC) { const LAS float* sn = sb + (t + 1) * SST;
;                         kk4n = *(const LAS f32x4*)(sn); nb4n = *(const LAS f32x4*)(sn + 64); w4n = *(const LAS f32x4*)(sn + 128); k4n = *(const LAS f32x4*)(sn + 192); r4n = *(const LAS f32x4*)(sn + 256); vn = vb[(t + 1) * SST]; }
;                     __builtin_amdgcn_sched_barrier(0x6);
;                     float sa = fmaf(S[3], kk4[3], fmaf(S[2], kk4[2], fmaf(S[1], kk4[1], S[0] * kk4[0])));
;                     const f32x4 Tm = S * w4 + k4 * v;
;                     sa = row16_sum(sa);
;                     S = Tm + nb4 * sa;
;                     float y = fmaf(S[3], r4[3], fmaf(S[2], r4[2], fmaf(S[1], r4[1], S[0] * r4[0]))); y = row16_sum(y);
;                     ysel = (cgp == (t & 15)) ? y : ysel;
;                     if ((t & 15) == 15) yb[(t - 15 + cgp) * 32 + rl] = ysel;
;                     kk4 = kk4n; nb4 = nb4n; w4 = w4n; k4 = k4n; r4 = r4n; v = vn; }
.LBB0_190:
	s_and_b32 s2, s67, 1
	s_mul_i32 s3, s2, 0xb000
	s_add_i32 s3, s94, s3
	v_add_u32_e32 v124, s3, v114
	v_add_u32_e32 v110, s3, v120
	ds_read_b128 v[136:139], v124 offset:0
	ds_read_b128 v[140:143], v124 offset:256
	ds_read_b128 v[144:147], v124 offset:512
	ds_read_b128 v[148:151], v124 offset:768
	ds_read_b128 v[152:155], v124 offset:1024
	ds_read_b32 v156, v110 offset:1280
	ds_read_b128 v[160:163], v124 offset:1408
	ds_read_b128 v[164:167], v124 offset:1664
	ds_read_b128 v[168:171], v124 offset:1920
	ds_read_b128 v[172:175], v124 offset:2176
	ds_read_b128 v[176:179], v124 offset:2432
	ds_read_b32 v158, v110 offset:2688
	ds_read_b128 v[188:191], v124 offset:2816
	ds_read_b128 v[192:195], v124 offset:3072
	ds_read_b128 v[196:199], v124 offset:3328
	ds_read_b128 v[200:203], v124 offset:3584
	ds_read_b128 v[204:207], v124 offset:3840
	ds_read_b32 v208, v110 offset:4096
	s_lshl_b32 s2, s2, 12
	s_add_i32 s63, s64, s2
	s_add_i32 s62, s67, 1
	s_andn2_b64 vcc, exec, s[60:61]
	v_add3_u32 v122, s63, v120, v118
	s_waitcnt lgkmcnt(12)
	v_mul_f32_e32 v44, v36, v136
	v_fmac_f32_e32 v44, v37, v137
	v_fmac_f32_e32 v44, v38, v138
	v_fmac_f32_e32 v44, v39, v139
	v_pk_mul_f32 v[40:41], v[148:149], v[156:157] op_sel_hi:[1,0]
	v_pk_mul_f32 v[42:43], v[150:151], v[156:157] op_sel_hi:[1,0]
	v_add_f32_dpp v2, v44, v44 quad_perm:[1,0,3,2] row_mask:0xf bank_mask:0xf bound_ctrl:1
	v_pk_fma_f32 v[40:41], v[36:37], v[144:145], v[40:41]
	v_pk_fma_f32 v[42:43], v[38:39], v[146:147], v[42:43]
	v_add_f32_dpp v2, v2, v2 quad_perm:[2,3,0,1] row_mask:0xf bank_mask:0xf bound_ctrl:1
	s_nop 0
	s_nop 0
	v_add_f32_dpp v2, v2, v2 row_ror:4 row_mask:0xf bank_mask:0xf bound_ctrl:1
	s_nop 0
	s_nop 0
	v_add_f32_dpp v2, v2, v2 row_ror:8 row_mask:0xf bank_mask:0xf bound_ctrl:1
	s_waitcnt lgkmcnt(6)
	v_pk_fma_f32 v[36:37], v[140:141], v[2:3], v[40:41] op_sel_hi:[1,0,1]
	v_pk_fma_f32 v[38:39], v[142:143], v[2:3], v[42:43] op_sel_hi:[1,0,1]
	v_mul_f32_e32 v44, v36, v160
	v_mul_f32_e32 v45, v152, v36
	v_fmac_f32_e32 v44, v37, v161
	v_fmac_f32_e32 v45, v37, v153
	v_fmac_f32_e32 v44, v38, v162
	v_fmac_f32_e32 v45, v38, v154
	v_fmac_f32_e32 v44, v39, v163
	v_fmac_f32_e32 v45, v39, v155
	v_pk_mul_f32 v[40:41], v[172:173], v[158:159] op_sel_hi:[1,0]
	v_pk_mul_f32 v[42:43], v[174:175], v[158:159] op_sel_hi:[1,0]
	v_add_f32_dpp v2, v44, v44 quad_perm:[1,0,3,2] row_mask:0xf bank_mask:0xf bound_ctrl:1
	v_pk_fma_f32 v[40:41], v[36:37], v[168:169], v[40:41]
	v_pk_fma_f32 v[42:43], v[38:39], v[170:171], v[42:43]
	v_add_f32_dpp v2, v2, v2 quad_perm:[2,3,0,1] row_mask:0xf bank_mask:0xf bound_ctrl:1
	ds_read_b128 v[136:139], v124 offset:4224
	ds_read_b128 v[140:143], v124 offset:4480
	ds_read_b128 v[144:147], v124 offset:4736
	v_add_f32_dpp v2, v2, v2 row_ror:4 row_mask:0xf bank_mask:0xf bound_ctrl:1
	ds_read_b128 v[148:151], v124 offset:4992
	ds_read_b128 v[152:155], v124 offset:5248
	ds_read_b32 v156, v110 offset:5504
	v_add_f32_dpp v2, v2, v2 row_ror:8 row_mask:0xf bank_mask:0xf bound_ctrl:1
	s_waitcnt lgkmcnt(6)
	v_pk_fma_f32 v[36:37], v[164:165], v[2:3], v[40:41] op_sel_hi:[1,0,1]
	v_pk_fma_f32 v[38:39], v[166:167], v[2:3], v[42:43] op_sel_hi:[1,0,1]
	v_mul_f32_e32 v44, v36, v188
	v_mul_f32_e32 v46, v176, v36
	v_fmac_f32_e32 v44, v37, v189
	v_fmac_f32_e32 v46, v37, v177
	v_fmac_f32_e32 v44, v38, v190
	v_fmac_f32_e32 v46, v38, v178
	v_fmac_f32_e32 v44, v39, v191
	v_fmac_f32_e32 v46, v39, v179
	v_pk_mul_f32 v[40:41], v[200:201], v[208:209] op_sel_hi:[1,0]
	v_pk_mul_f32 v[42:43], v[202:203], v[208:209] op_sel_hi:[1,0]
	v_add_f32_dpp v2, v44, v44 quad_perm:[1,0,3,2] row_mask:0xf bank_mask:0xf bound_ctrl:1
	v_pk_fma_f32 v[40:41], v[36:37], v[196:197], v[40:41]
	v_pk_fma_f32 v[42:43], v[38:39], v[198:199], v[42:43]
	v_add_f32_dpp v2, v2, v2 quad_perm:[2,3,0,1] row_mask:0xf bank_mask:0xf bound_ctrl:1
	ds_read_b128 v[160:163], v124 offset:5632
	ds_read_b128 v[164:167], v124 offset:5888
	ds_read_b128 v[168:171], v124 offset:6144
	v_add_f32_dpp v2, v2, v2 row_ror:4 row_mask:0xf bank_mask:0xf bound_ctrl:1
	ds_read_b128 v[172:175], v124 offset:6400
	ds_read_b128 v[176:179], v124 offset:6656
	ds_read_b32 v158, v110 offset:6912
	v_add_f32_dpp v2, v2, v2 row_ror:8 row_mask:0xf bank_mask:0xf bound_ctrl:1
	v_cndmask_b32_e64 v56, v45, v46, s[8:9]
	v_cndmask_b32_e64 v57, v46, v45, s[8:9]
	s_waitcnt lgkmcnt(6)
	v_pk_fma_f32 v[36:37], v[192:193], v[2:3], v[40:41] op_sel_hi:[1,0,1]
	v_pk_fma_f32 v[38:39], v[194:195], v[2:3], v[42:43] op_sel_hi:[1,0,1]
	v_add_f32_dpp v47, v57, v56 quad_perm:[1,0,3,2] row_mask:0xf bank_mask:0xf bound_ctrl:1
	v_mul_f32_e32 v44, v36, v136
	v_mul_f32_e32 v48, v204, v36
	v_fmac_f32_e32 v44, v37, v137
	v_fmac_f32_e32 v48, v37, v205
	v_fmac_f32_e32 v44, v38, v138
	v_fmac_f32_e32 v48, v38, v206
	v_fmac_f32_e32 v44, v39, v139
	v_fmac_f32_e32 v48, v39, v207
	v_pk_mul_f32 v[40:41], v[148:149], v[156:157] op_sel_hi:[1,0]
	v_pk_mul_f32 v[42:43], v[150:151], v[156:157] op_sel_hi:[1,0]
	v_add_f32_dpp v2, v44, v44 quad_perm:[1,0,3,2] row_mask:0xf bank_mask:0xf bound_ctrl:1
	v_pk_fma_f32 v[40:41], v[36:37], v[144:145], v[40:41]
	v_pk_fma_f32 v[42:43], v[38:39], v[146:147], v[42:43]
	v_add_f32_dpp v2, v2, v2 quad_perm:[2,3,0,1] row_mask:0xf bank_mask:0xf bound_ctrl:1
	ds_read_b128 v[188:191], v124 offset:7040
	ds_read_b128 v[192:195], v124 offset:7296
	ds_read_b128 v[196:199], v124 offset:7552
	v_add_f32_dpp v2, v2, v2 row_ror:4 row_mask:0xf bank_mask:0xf bound_ctrl:1
	ds_read_b128 v[200:203], v124 offset:7808
	ds_read_b128 v[204:207], v124 offset:8064
	ds_read_b32 v208, v110 offset:8320
	v_add_f32_dpp v2, v2, v2 row_ror:8 row_mask:0xf bank_mask:0xf bound_ctrl:1
	s_waitcnt lgkmcnt(6)
; #define LAS __attribute__((address_space(3)))
; __device__ __forceinline__ float row16_sum(float x) { x += dpp_mov<0xB1>(x); x += dpp_mov<0x4E>(x); x += dpp_mov<0x124>(x); x += dpp_mov<0x128>(x); return x; }
; __device__ __forceinline__ void up4(const u32x2 w, float (&f)[4]) { f[0] = bflo(w.x); f[1] = bfhi(w.x); f[2] = bflo(w.y); f[3] = bfhi(w.y); }
; __device__ __forceinline__ void scan_stage(const u32x2 (&pz)[8], LAS float* buf, float* RKB, size_t mrow0, int t0, int tid, int h, int half, ...
;     ...
;     up4(pz[0], zr); up4(pz[1], zk); up4(pz[2], zv); up4(pz[3], zrp); up4(pz[4], zkp); up4(pz[5], zvp); up4(pz[6], ew); up4(pz[7], ic);
;     f32x4 r, k2, v, kkv, w; float n2 = 0.f, rkb = 0.f;
; #pragma unroll
;     for (int e = 0; e < 4; ++e) { r[e] = zr[e] + (zrp[e] - zr[e]) * mu_r[e]; const float k = zk[e] + (zkp[e] - zk[e]) * mu_k[e]; v[e] = zv[e] + (zvp[e] - zv[e]) * mu_v[e];
;         kkv[e] = k * kkc[e]; n2 += kkv[e] * kkv[e]; k2[e] = k * (1.0f + (ic[e] - 1.0f) * kac[e]); w[e] = __builtin_amdgcn_exp2f(-1.4426950408889634f * ew[e]); rkb += r[e] * k2[e] * rkc[e]; }
; __device__ __forceinline__ void scan_phase(const KAS Args& a, LAS unsigned char* lds, int i, const int tid_, const int bid, const int nblk) {
;     ...
;                 for (int t = 0; t < TC; ++t) {
;                     f32x4 kk4n = kk4, nb4n = nb4, w4n = w4, k4n = k4, r4n = r4; float vn = v;
;                     if (t + 1 < TC) { const LAS float* sn = sb + (t + 1) * SST;
;                         kk4n = *(const LAS f32x4*)(sn); nb4n = *(const LAS f32x4*)(sn + 64); w4n = *(const LAS f32x4*)(sn + 128); k4n = *(const LAS f32x4*)(sn + 192); r4n = *(const LAS f32x4*)(sn + 256); vn = vb[(t + 1) * SST]; }
;                     __builtin_amdgcn_sched_barrier(0x6);
;                     float sa = fmaf(S[3], kk4[3], fmaf(S[2], kk4[2], fmaf(S[1], kk4[1], S[0] * kk4[0])));
;                     const f32x4 Tm = S * w4 + k4 * v;
;                     sa = row16_sum(sa);
;                     S = Tm + nb4 * sa;
;                     float y = fmaf(S[3], r4[3], fmaf(S[2], r4[2], fmaf(S[1], r4[1], S[0] * r4[0]))); y = row16_sum(y);
;                     ysel = (cgp == (t & 15)) ? y : ysel;
;                     if ((t & 15) == 15) yb[(t - 15 + cgp) * 32 + rl] = ysel;
;                     kk4 = kk4n; nb4 = nb4n; w4 = w4n; k4 = k4n; r4 = r4n; v = vn; }
	v_pk_fma_f32 v[36:37], v[140:141], v[2:3], v[40:41] op_sel_hi:[1,0,1]
	v_pk_fma_f32 v[38:39], v[142:143], v[2:3], v[42:43] op_sel_hi:[1,0,1]
	v_mul_f32_e32 v44, v36, v160
	v_mul_f32_e32 v49, v152, v36
	v_fmac_f32_e32 v44, v37, v161
	v_fmac_f32_e32 v49, v37, v153
	v_fmac_f32_e32 v44, v38, v162
	v_fmac_f32_e32 v49, v38, v154
	v_fmac_f32_e32 v44, v39, v163
	v_fmac_f32_e32 v49, v39, v155
	v_pk_mul_f32 v[40:41], v[172:173], v[158:159] op_sel_hi:[1,0]
	v_pk_mul_f32 v[42:43], v[174:175], v[158:159] op_sel_hi:[1,0]
	v_add_f32_dpp v2, v44, v44 quad_perm:[1,0,3,2] row_mask:0xf bank_mask:0xf bound_ctrl:1
	v_pk_fma_f32 v[40:41], v[36:37], v[168:169], v[40:41]
	v_pk_fma_f32 v[42:43], v[38:39], v[170:171], v[42:43]
	v_add_f32_dpp v2, v2, v2 quad_perm:[2,3,0,1] row_mask:0xf bank_mask:0xf bound_ctrl:1
	ds_read_b128 v[136:139], v124 offset:8448
	ds_read_b128 v[140:143], v124 offset:8704
	ds_read_b128 v[144:147], v124 offset:8960
	v_add_f32_dpp v2, v2, v2 row_ror:4 row_mask:0xf bank_mask:0xf bound_ctrl:1
	ds_read_b128 v[148:151], v124 offset:9216
	ds_read_b128 v[152:155], v124 offset:9472
	ds_read_b32 v156, v110 offset:9728
	v_add_f32_dpp v2, v2, v2 row_ror:8 row_mask:0xf bank_mask:0xf bound_ctrl:1
	v_cndmask_b32_e64 v56, v48, v49, s[8:9]
	v_cndmask_b32_e64 v57, v49, v48, s[8:9]
	s_waitcnt lgkmcnt(6)
	v_pk_fma_f32 v[36:37], v[164:165], v[2:3], v[40:41] op_sel_hi:[1,0,1]
	v_pk_fma_f32 v[38:39], v[166:167], v[2:3], v[42:43] op_sel_hi:[1,0,1]
	v_add_f32_dpp v50, v57, v56 quad_perm:[1,0,3,2] row_mask:0xf bank_mask:0xf bound_ctrl:1
	v_cndmask_b32_e64 v56, v47, v50, s[10:11]
	v_cndmask_b32_e64 v57, v50, v47, s[10:11]
	v_mul_f32_e32 v44, v36, v188
	v_mul_f32_e32 v52, v176, v36
	v_add_f32_dpp v51, v57, v56 quad_perm:[2,3,0,1] row_mask:0xf bank_mask:0xf bound_ctrl:1
	v_fmac_f32_e32 v44, v37, v189
	v_fmac_f32_e32 v52, v37, v177
	v_fmac_f32_e32 v44, v38, v190
	v_fmac_f32_e32 v52, v38, v178
	v_fmac_f32_e32 v44, v39, v191
	v_fmac_f32_e32 v52, v39, v179
	v_pk_mul_f32 v[40:41], v[200:201], v[208:209] op_sel_hi:[1,0]
	v_pk_mul_f32 v[42:43], v[202:203], v[208:209] op_sel_hi:[1,0]
	v_add_f32_dpp v2, v44, v44 quad_perm:[1,0,3,2] row_mask:0xf bank_mask:0xf bound_ctrl:1
	v_pk_fma_f32 v[40:41], v[36:37], v[196:197], v[40:41]
	v_pk_fma_f32 v[42:43], v[38:39], v[198:199], v[42:43]
	v_add_f32_dpp v2, v2, v2 quad_perm:[2,3,0,1] row_mask:0xf bank_mask:0xf bound_ctrl:1
	ds_read_b128 v[160:163], v124 offset:9856
	ds_read_b128 v[164:167], v124 offset:10112
	ds_read_b128 v[168:171], v124 offset:10368
	v_add_f32_dpp v2, v2, v2 row_ror:4 row_mask:0xf bank_mask:0xf bound_ctrl:1
	ds_read_b128 v[172:175], v124 offset:10624
	ds_read_b128 v[176:179], v124 offset:10880
	ds_read_b32 v158, v110 offset:11136
	v_add_f32_dpp v2, v2, v2 row_ror:8 row_mask:0xf bank_mask:0xf bound_ctrl:1
	s_waitcnt lgkmcnt(6)
	v_pk_fma_f32 v[36:37], v[192:193], v[2:3], v[40:41] op_sel_hi:[1,0,1]
	v_pk_fma_f32 v[38:39], v[194:195], v[2:3], v[42:43] op_sel_hi:[1,0,1]
	v_mul_f32_e32 v44, v36, v136
	v_mul_f32_e32 v53, v204, v36
	v_fmac_f32_e32 v44, v37, v137
	v_fmac_f32_e32 v53, v37, v205
	v_fmac_f32_e32 v44, v38, v138
	v_fmac_f32_e32 v53, v38, v206
	v_fmac_f32_e32 v44, v39, v139
	v_fmac_f32_e32 v53, v39, v207
	v_pk_mul_f32 v[40:41], v[148:149], v[156:157] op_sel_hi:[1,0]
	v_pk_mul_f32 v[42:43], v[150:151], v[156:157] op_sel_hi:[1,0]
	v_add_f32_dpp v2, v44, v44 quad_perm:[1,0,3,2] row_mask:0xf bank_mask:0xf bound_ctrl:1
	v_pk_fma_f32 v[40:41], v[36:37], v[144:145], v[40:41]
	v_pk_fma_f32 v[42:43], v[38:39], v[146:147], v[42:43]
	v_add_f32_dpp v2, v2, v2 quad_perm:[2,3,0,1] row_mask:0xf bank_mask:0xf bound_ctrl:1
	s_waitcnt vmcnt(4)
	v_lshlrev_b32_e32 v28, 16, v80
	ds_read_b128 v[188:191], v124 offset:11264
	ds_read_b128 v[192:195], v124 offset:11520
	ds_read_b128 v[196:199], v124 offset:11776
	v_add_f32_dpp v2, v2, v2 row_ror:4 row_mask:0xf bank_mask:0xf bound_ctrl:1
	ds_read_b128 v[200:203], v124 offset:12032
	ds_read_b128 v[204:207], v124 offset:12288
	ds_read_b32 v208, v110 offset:12544
	v_add_f32_dpp v2, v2, v2 row_ror:8 row_mask:0xf bank_mask:0xf bound_ctrl:1
	v_cndmask_b32_e64 v56, v52, v53, s[8:9]
	v_cndmask_b32_e64 v57, v53, v52, s[8:9]
	v_and_b32_e32 v29, 0xffff0000, v80
	v_lshlrev_b32_e32 v30, 16, v86
	s_waitcnt lgkmcnt(6)
	v_pk_fma_f32 v[36:37], v[140:141], v[2:3], v[40:41] op_sel_hi:[1,0,1]
	v_pk_fma_f32 v[38:39], v[142:143], v[2:3], v[42:43] op_sel_hi:[1,0,1]
	v_add_f32_dpp v54, v57, v56 quad_perm:[1,0,3,2] row_mask:0xf bank_mask:0xf bound_ctrl:1
	v_mul_f32_e32 v44, v36, v160
	v_mul_f32_e32 v55, v152, v36
	v_fmac_f32_e32 v44, v37, v161
	v_fmac_f32_e32 v55, v37, v153
	v_fmac_f32_e32 v44, v38, v162
	v_fmac_f32_e32 v55, v38, v154
	v_fmac_f32_e32 v44, v39, v163
	v_fmac_f32_e32 v55, v39, v155
	v_pk_mul_f32 v[40:41], v[172:173], v[158:159] op_sel_hi:[1,0]
	v_pk_mul_f32 v[42:43], v[174:175], v[158:159] op_sel_hi:[1,0]
	v_add_f32_dpp v2, v44, v44 quad_perm:[1,0,3,2] row_mask:0xf bank_mask:0xf bound_ctrl:1
	v_pk_fma_f32 v[40:41], v[36:37], v[168:169], v[40:41]
	v_pk_fma_f32 v[42:43], v[38:39], v[170:171], v[42:43]
	v_add_f32_dpp v2, v2, v2 quad_perm:[2,3,0,1] row_mask:0xf bank_mask:0xf bound_ctrl:1
	v_and_b32_e32 v31, 0xffff0000, v86
	v_pk_add_f32 v[30:31], v[30:31], v[28:29] neg_lo:[0,1] neg_hi:[0,1]
	ds_read_b128 v[136:139], v124 offset:12672
	ds_read_b128 v[140:143], v124 offset:12928
	ds_read_b128 v[144:147], v124 offset:13184
	v_add_f32_dpp v2, v2, v2 row_ror:4 row_mask:0xf bank_mask:0xf bound_ctrl:1
	ds_read_b128 v[148:151], v124 offset:13440
	ds_read_b128 v[152:155], v124 offset:13696
	ds_read_b32 v156, v110 offset:13952
	v_add_f32_dpp v2, v2, v2 row_ror:8 row_mask:0xf bank_mask:0xf bound_ctrl:1
	s_waitcnt vmcnt(3)
; #define LAS __attribute__((address_space(3)))
; __device__ __forceinline__ float row16_sum(float x) { x += dpp_mov<0xB1>(x); x += dpp_mov<0x4E>(x); x += dpp_mov<0x124>(x); x += dpp_mov<0x128>(x); return x; }
; __device__ __forceinline__ void up4(const u32x2 w, float (&f)[4]) { f[0] = bflo(w.x); f[1] = bfhi(w.x); f[2] = bflo(w.y); f[3] = bfhi(w.y); }
; __device__ __forceinline__ void scan_stage(const u32x2 (&pz)[8], LAS float* buf, float* RKB, size_t mrow0, int t0, int tid, int h, int half, ...
;     ...
;     up4(pz[0], zr); up4(pz[1], zk); up4(pz[2], zv); up4(pz[3], zrp); up4(pz[4], zkp); up4(pz[5], zvp); up4(pz[6], ew); up4(pz[7], ic);
;     f32x4 r, k2, v, kkv, w; float n2 = 0.f, rkb = 0.f;
; #pragma unroll
;     for (int e = 0; e < 4; ++e) { r[e] = zr[e] + (zrp[e] - zr[e]) * mu_r[e]; const float k = zk[e] + (zkp[e] - zk[e]) * mu_k[e]; v[e] = zv[e] + (zvp[e] - zv[e]) * mu_v[e];
;         kkv[e] = k * kkc[e]; n2 += kkv[e] * kkv[e]; k2[e] = k * (1.0f + (ic[e] - 1.0f) * kac[e]); w[e] = __builtin_amdgcn_exp2f(-1.4426950408889634f * ew[e]); rkb += r[e] * k2[e] * rkc[e]; }
; __device__ __forceinline__ void scan_phase(const KAS Args& a, LAS unsigned char* lds, int i, const int tid_, const int bid, const int nblk) {
;     ...
;                 for (int t = 0; t < TC; ++t) {
;                     f32x4 kk4n = kk4, nb4n = nb4, w4n = w4, k4n = k4, r4n = r4; float vn = v;
;                     if (t + 1 < TC) { const LAS float* sn = sb + (t + 1) * SST;
;                         kk4n = *(const LAS f32x4*)(sn); nb4n = *(const LAS f32x4*)(sn + 64); w4n = *(const LAS f32x4*)(sn + 128); k4n = *(const LAS f32x4*)(sn + 192); r4n = *(const LAS f32x4*)(sn + 256); vn = vb[(t + 1) * SST]; }
;                     __builtin_amdgcn_sched_barrier(0x6);
;                     float sa = fmaf(S[3], kk4[3], fmaf(S[2], kk4[2], fmaf(S[1], kk4[1], S[0] * kk4[0])));
;                     const f32x4 Tm = S * w4 + k4 * v;
;                     sa = row16_sum(sa);
;                     S = Tm + nb4 * sa;
;                     float y = fmaf(S[3], r4[3], fmaf(S[2], r4[2], fmaf(S[1], r4[1], S[0] * r4[0]))); y = row16_sum(y);
;                     ysel = (cgp == (t & 15)) ? y : ysel;
;                     if ((t & 15) == 15) yb[(t - 15 + cgp) * 32 + rl] = ysel;
;                     kk4 = kk4n; nb4 = nb4n; w4 = w4n; k4 = k4n; r4 = r4n; v = vn; }
	v_lshlrev_b32_e32 v32, 16, v88
	s_waitcnt lgkmcnt(6)
	v_pk_fma_f32 v[36:37], v[164:165], v[2:3], v[40:41] op_sel_hi:[1,0,1]
	v_pk_fma_f32 v[38:39], v[166:167], v[2:3], v[42:43] op_sel_hi:[1,0,1]
	v_mul_f32_e32 v44, v36, v188
	v_mul_f32_e32 v58, v176, v36
	v_fmac_f32_e32 v44, v37, v189
	v_fmac_f32_e32 v58, v37, v177
	v_fmac_f32_e32 v44, v38, v190
	v_fmac_f32_e32 v58, v38, v178
	v_fmac_f32_e32 v44, v39, v191
	v_fmac_f32_e32 v58, v39, v179
	v_pk_mul_f32 v[40:41], v[200:201], v[208:209] op_sel_hi:[1,0]
	v_pk_mul_f32 v[42:43], v[202:203], v[208:209] op_sel_hi:[1,0]
	v_add_f32_dpp v2, v44, v44 quad_perm:[1,0,3,2] row_mask:0xf bank_mask:0xf bound_ctrl:1
	v_pk_fma_f32 v[40:41], v[36:37], v[196:197], v[40:41]
	v_pk_fma_f32 v[42:43], v[38:39], v[198:199], v[42:43]
	v_add_f32_dpp v2, v2, v2 quad_perm:[2,3,0,1] row_mask:0xf bank_mask:0xf bound_ctrl:1
	v_pk_fma_f32 v[28:29], v[16:17], v[30:31], v[28:29]
	v_lshlrev_b32_e32 v30, 16, v82
	ds_read_b128 v[160:163], v124 offset:14080
	ds_read_b128 v[164:167], v124 offset:14336
	ds_read_b128 v[168:171], v124 offset:14592
	v_add_f32_dpp v2, v2, v2 row_ror:4 row_mask:0xf bank_mask:0xf bound_ctrl:1
	ds_read_b128 v[172:175], v124 offset:14848
	ds_read_b128 v[176:179], v124 offset:15104
	ds_read_b32 v158, v110 offset:15360
	v_add_f32_dpp v2, v2, v2 row_ror:8 row_mask:0xf bank_mask:0xf bound_ctrl:1
	v_cndmask_b32_e64 v56, v55, v58, s[8:9]
	v_cndmask_b32_e64 v57, v58, v55, s[8:9]
	v_and_b32_e32 v31, 0xffff0000, v82
	v_and_b32_e32 v33, 0xffff0000, v88
	s_waitcnt lgkmcnt(6)
	v_pk_fma_f32 v[36:37], v[192:193], v[2:3], v[40:41] op_sel_hi:[1,0,1]
	v_pk_fma_f32 v[38:39], v[194:195], v[2:3], v[42:43] op_sel_hi:[1,0,1]
	v_add_f32_dpp v59, v57, v56 quad_perm:[1,0,3,2] row_mask:0xf bank_mask:0xf bound_ctrl:1
	v_cndmask_b32_e64 v56, v54, v59, s[10:11]
	v_cndmask_b32_e64 v57, v59, v54, s[10:11]
	v_mul_f32_e32 v44, v36, v136
	v_mul_f32_e32 v62, v204, v36
	v_add_f32_dpp v60, v57, v56 quad_perm:[2,3,0,1] row_mask:0xf bank_mask:0xf bound_ctrl:1
	v_fmac_f32_e32 v44, v37, v137
	v_fmac_f32_e32 v62, v37, v205
	v_cndmask_b32_e64 v56, v51, v60, s[12:13]
	v_fmac_f32_e32 v44, v38, v138
	v_fmac_f32_e32 v62, v38, v206
	v_cndmask_b32_e64 v57, v60, v51, s[12:13]
	v_fmac_f32_e32 v44, v39, v139
	v_fmac_f32_e32 v62, v39, v207
	v_pk_mul_f32 v[40:41], v[148:149], v[156:157] op_sel_hi:[1,0]
	v_pk_mul_f32 v[42:43], v[150:151], v[156:157] op_sel_hi:[1,0]
	v_add_f32_dpp v2, v44, v44 quad_perm:[1,0,3,2] row_mask:0xf bank_mask:0xf bound_ctrl:1
	v_pk_fma_f32 v[40:41], v[36:37], v[144:145], v[40:41]
	v_pk_fma_f32 v[42:43], v[38:39], v[146:147], v[42:43]
	v_add_f32_dpp v2, v2, v2 quad_perm:[2,3,0,1] row_mask:0xf bank_mask:0xf bound_ctrl:1
	s_waitcnt vmcnt(0)
	v_lshlrev_b32_e32 v210, 16, v94
	ds_read_b128 v[188:191], v124 offset:15488
	ds_read_b128 v[192:195], v124 offset:15744
	ds_read_b128 v[196:199], v124 offset:16000
	v_add_f32_dpp v2, v2, v2 row_ror:4 row_mask:0xf bank_mask:0xf bound_ctrl:1
	ds_read_b128 v[200:203], v124 offset:16256
	ds_read_b128 v[204:207], v124 offset:16512
	ds_read_b32 v208, v110 offset:16768
	v_add_f32_dpp v2, v2, v2 row_ror:8 row_mask:0xf bank_mask:0xf bound_ctrl:1
	v_add_f32_dpp v61, v57, v56 row_shl:4 row_mask:0xf bank_mask:0x5
	v_and_b32_e32 v211, 0xffff0000, v94
	v_pk_add_f32 v[32:33], v[32:33], v[30:31] neg_lo:[0,1] neg_hi:[0,1]
	s_waitcnt lgkmcnt(6)
	v_pk_fma_f32 v[36:37], v[140:141], v[2:3], v[40:41] op_sel_hi:[1,0,1]
	v_pk_fma_f32 v[38:39], v[142:143], v[2:3], v[42:43] op_sel_hi:[1,0,1]
	v_add_f32_dpp v61, v57, v56 row_shr:4 row_mask:0xf bank_mask:0xa
	v_mul_f32_e32 v44, v36, v160
	v_mul_f32_e32 v63, v152, v36
	v_fmac_f32_e32 v44, v37, v161
	v_fmac_f32_e32 v63, v37, v153
	v_fmac_f32_e32 v44, v38, v162
	v_fmac_f32_e32 v63, v38, v154
	v_fmac_f32_e32 v44, v39, v163
	v_fmac_f32_e32 v63, v39, v155
	v_pk_mul_f32 v[40:41], v[172:173], v[158:159] op_sel_hi:[1,0]
	v_pk_mul_f32 v[42:43], v[174:175], v[158:159] op_sel_hi:[1,0]
	v_add_f32_dpp v2, v44, v44 quad_perm:[1,0,3,2] row_mask:0xf bank_mask:0xf bound_ctrl:1
	v_pk_fma_f32 v[40:41], v[36:37], v[168:169], v[40:41]
	v_pk_fma_f32 v[42:43], v[38:39], v[170:171], v[42:43]
	v_add_f32_dpp v2, v2, v2 quad_perm:[2,3,0,1] row_mask:0xf bank_mask:0xf bound_ctrl:1
	v_lshlrev_b32_e32 v216, 16, v89
	v_pk_fma_f32 v[30:31], v[20:21], v[32:33], v[30:31]
	ds_read_b128 v[136:139], v124 offset:16896
	ds_read_b128 v[140:143], v124 offset:17152
	ds_read_b128 v[144:147], v124 offset:17408
	v_add_f32_dpp v2, v2, v2 row_ror:4 row_mask:0xf bank_mask:0xf bound_ctrl:1
	ds_read_b128 v[148:151], v124 offset:17664
	ds_read_b128 v[152:155], v124 offset:17920
	ds_read_b32 v156, v110 offset:18176
	v_add_f32_dpp v2, v2, v2 row_ror:8 row_mask:0xf bank_mask:0xf bound_ctrl:1
	v_cndmask_b32_e64 v56, v62, v63, s[8:9]
	v_cndmask_b32_e64 v57, v63, v62, s[8:9]
	v_pk_add_f32 v[32:33], v[210:211], -1.0 op_sel_hi:[1,0]
	v_pk_mul_f32 v[212:213], v[12:13], v[30:31]
	s_waitcnt lgkmcnt(6)
	v_pk_fma_f32 v[36:37], v[164:165], v[2:3], v[40:41] op_sel_hi:[1,0,1]
	v_pk_fma_f32 v[38:39], v[166:167], v[2:3], v[42:43] op_sel_hi:[1,0,1]
	v_add_f32_dpp v64, v57, v56 quad_perm:[1,0,3,2] row_mask:0xf bank_mask:0xf bound_ctrl:1
	v_mul_f32_e32 v44, v36, v188
	v_mul_f32_e32 v65, v176, v36
	v_fmac_f32_e32 v44, v37, v189
	v_fmac_f32_e32 v65, v37, v177
	v_fmac_f32_e32 v44, v38, v190
	v_fmac_f32_e32 v65, v38, v178
	v_fmac_f32_e32 v44, v39, v191
	v_fmac_f32_e32 v65, v39, v179
	v_pk_mul_f32 v[40:41], v[200:201], v[208:209] op_sel_hi:[1,0]
	v_pk_mul_f32 v[42:43], v[202:203], v[208:209] op_sel_hi:[1,0]
	v_add_f32_dpp v2, v44, v44 quad_perm:[1,0,3,2] row_mask:0xf bank_mask:0xf bound_ctrl:1
	v_pk_fma_f32 v[40:41], v[36:37], v[196:197], v[40:41]
	v_pk_fma_f32 v[42:43], v[38:39], v[198:199], v[42:43]
	v_add_f32_dpp v2, v2, v2 quad_perm:[2,3,0,1] row_mask:0xf bank_mask:0xf bound_ctrl:1
	v_pk_fma_f32 v[32:33], v[24:25], v[32:33], 1.0 op_sel_hi:[1,1,0]
	v_and_b32_e32 v217, 0xffff0000, v89
	ds_read_b128 v[160:163], v124 offset:18304
	ds_read_b128 v[164:167], v124 offset:18560
	ds_read_b128 v[168:171], v124 offset:18816
	v_add_f32_dpp v2, v2, v2 row_ror:4 row_mask:0xf bank_mask:0xf bound_ctrl:1
	ds_read_b128 v[172:175], v124 offset:19072
	ds_read_b128 v[176:179], v124 offset:19328
	ds_read_b32 v158, v110 offset:19584
	v_add_f32_dpp v2, v2, v2 row_ror:8 row_mask:0xf bank_mask:0xf bound_ctrl:1
	v_pk_mul_f32 v[32:33], v[30:31], v[32:33]
	v_lshlrev_b32_e32 v30, 16, v81
	s_waitcnt lgkmcnt(6)
; #define LAS __attribute__((address_space(3)))
; __device__ __forceinline__ float row16_sum(float x) { x += dpp_mov<0xB1>(x); x += dpp_mov<0x4E>(x); x += dpp_mov<0x124>(x); x += dpp_mov<0x128>(x); return x; }
; __device__ __forceinline__ void scan_stage(const u32x2 (&pz)[8], LAS float* buf, float* RKB, size_t mrow0, int t0, int tid, int h, int half, ...
;     ...
;     for (int e = 0; e < 4; ++e) { r[e] = zr[e] + (zrp[e] - zr[e]) * mu_r[e]; const float k = zk[e] + (zkp[e] - zk[e]) * mu_k[e]; v[e] = zv[e] + (zvp[e] - zv[e]) * mu_v[e];
;         kkv[e] = k * kkc[e]; n2 += kkv[e] * kkv[e]; k2[e] = k * (1.0f + (ic[e] - 1.0f) * kac[e]); w[e] = __builtin_amdgcn_exp2f(-1.4426950408889634f * ew[e]); rkb += r[e] * k2[e] * rkc[e]; }
; __device__ __forceinline__ void scan_phase(const KAS Args& a, LAS unsigned char* lds, int i, const int tid_, const int bid, const int nblk) {
;     ...
;                 for (int t = 0; t < TC; ++t) {
;                     f32x4 kk4n = kk4, nb4n = nb4, w4n = w4, k4n = k4, r4n = r4; float vn = v;
;                     if (t + 1 < TC) { const LAS float* sn = sb + (t + 1) * SST;
;                         kk4n = *(const LAS f32x4*)(sn); nb4n = *(const LAS f32x4*)(sn + 64); w4n = *(const LAS f32x4*)(sn + 128); k4n = *(const LAS f32x4*)(sn + 192); r4n = *(const LAS f32x4*)(sn + 256); vn = vb[(t + 1) * SST]; }
;                     __builtin_amdgcn_sched_barrier(0x6);
;                     float sa = fmaf(S[3], kk4[3], fmaf(S[2], kk4[2], fmaf(S[1], kk4[1], S[0] * kk4[0])));
;                     const f32x4 Tm = S * w4 + k4 * v;
;                     sa = row16_sum(sa);
;                     S = Tm + nb4 * sa;
;                     float y = fmaf(S[3], r4[3], fmaf(S[2], r4[2], fmaf(S[1], r4[1], S[0] * r4[0]))); y = row16_sum(y);
;                     ysel = (cgp == (t & 15)) ? y : ysel;
;                     if ((t & 15) == 15) yb[(t - 15 + cgp) * 32 + rl] = ysel;
;                     kk4 = kk4n; nb4 = nb4n; w4 = w4n; k4 = k4n; r4 = r4n; v = vn; }
	v_pk_fma_f32 v[36:37], v[192:193], v[2:3], v[40:41] op_sel_hi:[1,0,1]
	v_pk_fma_f32 v[38:39], v[194:195], v[2:3], v[42:43] op_sel_hi:[1,0,1]
	v_mul_f32_e32 v44, v36, v136
	v_mul_f32_e32 v66, v204, v36
	v_fmac_f32_e32 v44, v37, v137
	v_fmac_f32_e32 v66, v37, v205
	v_fmac_f32_e32 v44, v38, v138
	v_fmac_f32_e32 v66, v38, v206
	v_fmac_f32_e32 v44, v39, v139
	v_fmac_f32_e32 v66, v39, v207
	v_pk_mul_f32 v[40:41], v[148:149], v[156:157] op_sel_hi:[1,0]
	v_pk_mul_f32 v[42:43], v[150:151], v[156:157] op_sel_hi:[1,0]
	v_add_f32_dpp v2, v44, v44 quad_perm:[1,0,3,2] row_mask:0xf bank_mask:0xf bound_ctrl:1
	v_pk_fma_f32 v[40:41], v[36:37], v[144:145], v[40:41]
	v_pk_fma_f32 v[42:43], v[38:39], v[146:147], v[42:43]
	v_add_f32_dpp v2, v2, v2 quad_perm:[2,3,0,1] row_mask:0xf bank_mask:0xf bound_ctrl:1
	v_pk_mul_f32 v[34:35], v[28:29], v[32:33]
	v_and_b32_e32 v31, 0xffff0000, v81
	ds_read_b128 v[188:191], v124 offset:19712
	ds_read_b128 v[192:195], v124 offset:19968
	ds_read_b128 v[196:199], v124 offset:20224
	v_add_f32_dpp v2, v2, v2 row_ror:4 row_mask:0xf bank_mask:0xf bound_ctrl:1
	ds_read_b128 v[200:203], v124 offset:20480
	ds_read_b128 v[204:207], v124 offset:20736
	ds_read_b32 v208, v110 offset:20992
	v_add_f32_dpp v2, v2, v2 row_ror:8 row_mask:0xf bank_mask:0xf bound_ctrl:1
	v_cndmask_b32_e64 v56, v65, v66, s[8:9]
	v_cndmask_b32_e64 v57, v66, v65, s[8:9]
	v_fma_f32 v224, v4, v34, 0
	v_fmac_f32_e32 v224, v5, v35
	s_waitcnt lgkmcnt(6)
	v_pk_fma_f32 v[36:37], v[140:141], v[2:3], v[40:41] op_sel_hi:[1,0,1]
	v_pk_fma_f32 v[38:39], v[142:143], v[2:3], v[42:43] op_sel_hi:[1,0,1]
	v_add_f32_dpp v67, v57, v56 quad_perm:[1,0,3,2] row_mask:0xf bank_mask:0xf bound_ctrl:1
	v_cndmask_b32_e64 v56, v64, v67, s[10:11]
	v_cndmask_b32_e64 v57, v67, v64, s[10:11]
	v_mul_f32_e32 v44, v36, v160
	v_mul_f32_e32 v46, v152, v36
	v_add_f32_dpp v45, v57, v56 quad_perm:[2,3,0,1] row_mask:0xf bank_mask:0xf bound_ctrl:1
	v_fmac_f32_e32 v44, v37, v161
	v_fmac_f32_e32 v46, v37, v153
	v_fmac_f32_e32 v44, v38, v162
	v_fmac_f32_e32 v46, v38, v154
	v_fmac_f32_e32 v44, v39, v163
	v_fmac_f32_e32 v46, v39, v155
	v_pk_mul_f32 v[40:41], v[172:173], v[158:159] op_sel_hi:[1,0]
	v_pk_mul_f32 v[42:43], v[174:175], v[158:159] op_sel_hi:[1,0]
	v_add_f32_dpp v2, v44, v44 quad_perm:[1,0,3,2] row_mask:0xf bank_mask:0xf bound_ctrl:1
	v_pk_fma_f32 v[40:41], v[36:37], v[168:169], v[40:41]
	v_pk_fma_f32 v[42:43], v[38:39], v[170:171], v[42:43]
	v_add_f32_dpp v2, v2, v2 quad_perm:[2,3,0,1] row_mask:0xf bank_mask:0xf bound_ctrl:1
	v_lshlrev_b32_e32 v34, 16, v87
	v_and_b32_e32 v35, 0xffff0000, v87
	ds_read_b128 v[136:139], v124 offset:21120
	ds_read_b128 v[140:143], v124 offset:21376
	ds_read_b128 v[144:147], v124 offset:21632
	v_add_f32_dpp v2, v2, v2 row_ror:4 row_mask:0xf bank_mask:0xf bound_ctrl:1
	ds_read_b128 v[148:151], v124 offset:21888
	ds_read_b128 v[152:155], v124 offset:22144
	ds_read_b32 v156, v110 offset:22400
	v_add_f32_dpp v2, v2, v2 row_ror:8 row_mask:0xf bank_mask:0xf bound_ctrl:1
	v_pk_add_f32 v[34:35], v[34:35], v[30:31] neg_lo:[0,1] neg_hi:[0,1]
	v_lshlrev_b32_e32 v214, 16, v95
	s_waitcnt lgkmcnt(6)
	v_pk_fma_f32 v[36:37], v[164:165], v[2:3], v[40:41] op_sel_hi:[1,0,1]
	v_pk_fma_f32 v[38:39], v[166:167], v[2:3], v[42:43] op_sel_hi:[1,0,1]
	v_mul_f32_e32 v44, v36, v188
	v_mul_f32_e32 v48, v176, v36
	v_fmac_f32_e32 v44, v37, v189
	v_fmac_f32_e32 v48, v37, v177
	v_fmac_f32_e32 v44, v38, v190
	v_fmac_f32_e32 v48, v38, v178
	v_fmac_f32_e32 v44, v39, v191
	v_fmac_f32_e32 v48, v39, v179
	v_pk_mul_f32 v[40:41], v[200:201], v[208:209] op_sel_hi:[1,0]
	v_pk_mul_f32 v[42:43], v[202:203], v[208:209] op_sel_hi:[1,0]
	v_add_f32_dpp v2, v44, v44 quad_perm:[1,0,3,2] row_mask:0xf bank_mask:0xf bound_ctrl:1
	v_pk_fma_f32 v[40:41], v[36:37], v[196:197], v[40:41]
	v_pk_fma_f32 v[42:43], v[38:39], v[198:199], v[42:43]
	v_add_f32_dpp v2, v2, v2 quad_perm:[2,3,0,1] row_mask:0xf bank_mask:0xf bound_ctrl:1
	v_pk_fma_f32 v[30:31], v[18:19], v[34:35], v[30:31]
	v_lshlrev_b32_e32 v34, 16, v83
	ds_read_b128 v[160:163], v124 offset:22528
	ds_read_b128 v[164:167], v124 offset:22784
	ds_read_b128 v[168:171], v124 offset:23040
	v_add_f32_dpp v2, v2, v2 row_ror:4 row_mask:0xf bank_mask:0xf bound_ctrl:1
	ds_read_b128 v[172:175], v124 offset:23296
	ds_read_b128 v[176:179], v124 offset:23552
	ds_read_b32 v158, v110 offset:23808
	v_add_f32_dpp v2, v2, v2 row_ror:8 row_mask:0xf bank_mask:0xf bound_ctrl:1
	v_cndmask_b32_e64 v56, v46, v48, s[8:9]
	v_cndmask_b32_e64 v57, v48, v46, s[8:9]
	v_and_b32_e32 v35, 0xffff0000, v83
	v_and_b32_e32 v215, 0xffff0000, v95
	s_waitcnt lgkmcnt(6)
	v_pk_fma_f32 v[36:37], v[192:193], v[2:3], v[40:41] op_sel_hi:[1,0,1]
	v_pk_fma_f32 v[38:39], v[194:195], v[2:3], v[42:43] op_sel_hi:[1,0,1]
	v_add_f32_dpp v49, v57, v56 quad_perm:[1,0,3,2] row_mask:0xf bank_mask:0xf bound_ctrl:1
	v_mul_f32_e32 v44, v36, v136
	v_mul_f32_e32 v47, v204, v36
	v_fmac_f32_e32 v44, v37, v137
	v_fmac_f32_e32 v47, v37, v205
	v_fmac_f32_e32 v44, v38, v138
	v_fmac_f32_e32 v47, v38, v206
	v_fmac_f32_e32 v44, v39, v139
	v_fmac_f32_e32 v47, v39, v207
	v_pk_mul_f32 v[40:41], v[148:149], v[156:157] op_sel_hi:[1,0]
	v_pk_mul_f32 v[42:43], v[150:151], v[156:157] op_sel_hi:[1,0]
	v_add_f32_dpp v2, v44, v44 quad_perm:[1,0,3,2] row_mask:0xf bank_mask:0xf bound_ctrl:1
	v_pk_fma_f32 v[40:41], v[36:37], v[144:145], v[40:41]
	v_pk_fma_f32 v[42:43], v[38:39], v[146:147], v[42:43]
	v_add_f32_dpp v2, v2, v2 quad_perm:[2,3,0,1] row_mask:0xf bank_mask:0xf bound_ctrl:1
	v_pk_add_f32 v[216:217], v[216:217], v[34:35] neg_lo:[0,1] neg_hi:[0,1]
	v_pk_mul_f32 v[218:219], v[212:213], v[212:213]
	ds_read_b128 v[188:191], v124 offset:23936
	ds_read_b128 v[192:195], v124 offset:24192
	ds_read_b128 v[196:199], v124 offset:24448
	v_add_f32_dpp v2, v2, v2 row_ror:4 row_mask:0xf bank_mask:0xf bound_ctrl:1
	ds_read_b128 v[200:203], v124 offset:24704
	ds_read_b128 v[204:207], v124 offset:24960
	ds_read_b32 v208, v110 offset:25216
	v_add_f32_dpp v2, v2, v2 row_ror:8 row_mask:0xf bank_mask:0xf bound_ctrl:1
	v_pk_fma_f32 v[216:217], v[22:23], v[216:217], v[34:35]
	v_pk_add_f32 v[34:35], v[214:215], -1.0 op_sel_hi:[1,0]
	s_waitcnt lgkmcnt(6)
; #define LAS __attribute__((address_space(3)))
; __device__ __forceinline__ float row16_sum(float x) { x += dpp_mov<0xB1>(x); x += dpp_mov<0x4E>(x); x += dpp_mov<0x124>(x); x += dpp_mov<0x128>(x); return x; }
; __device__ __forceinline__ void scan_stage(const u32x2 (&pz)[8], LAS float* buf, float* RKB, size_t mrow0, int t0, int tid, int h, int half, ...
;     ...
;     for (int e = 0; e < 4; ++e) { r[e] = zr[e] + (zrp[e] - zr[e]) * mu_r[e]; const float k = zk[e] + (zkp[e] - zk[e]) * mu_k[e]; v[e] = zv[e] + (zvp[e] - zv[e]) * mu_v[e];
;         kkv[e] = k * kkc[e]; n2 += kkv[e] * kkv[e]; k2[e] = k * (1.0f + (ic[e] - 1.0f) * kac[e]); w[e] = __builtin_amdgcn_exp2f(-1.4426950408889634f * ew[e]); rkb += r[e] * k2[e] * rkc[e]; }
; __device__ __forceinline__ void scan_phase(const KAS Args& a, LAS unsigned char* lds, int i, const int tid_, const int bid, const int nblk) {
;     ...
;                 for (int t = 0; t < TC; ++t) {
;                     f32x4 kk4n = kk4, nb4n = nb4, w4n = w4, k4n = k4, r4n = r4; float vn = v;
;                     if (t + 1 < TC) { const LAS float* sn = sb + (t + 1) * SST;
;                         kk4n = *(const LAS f32x4*)(sn); nb4n = *(const LAS f32x4*)(sn + 64); w4n = *(const LAS f32x4*)(sn + 128); k4n = *(const LAS f32x4*)(sn + 192); r4n = *(const LAS f32x4*)(sn + 256); vn = vb[(t + 1) * SST]; }
;                     __builtin_amdgcn_sched_barrier(0x6);
;                     float sa = fmaf(S[3], kk4[3], fmaf(S[2], kk4[2], fmaf(S[1], kk4[1], S[0] * kk4[0])));
;                     const f32x4 Tm = S * w4 + k4 * v;
;                     sa = row16_sum(sa);
;                     S = Tm + nb4 * sa;
;                     float y = fmaf(S[3], r4[3], fmaf(S[2], r4[2], fmaf(S[1], r4[1], S[0] * r4[0]))); y = row16_sum(y);
;                     ysel = (cgp == (t & 15)) ? y : ysel;
;                     if ((t & 15) == 15) yb[(t - 15 + cgp) * 32 + rl] = ysel;
;                     kk4 = kk4n; nb4 = nb4n; w4 = w4n; k4 = k4n; r4 = r4n; v = vn; }
	v_pk_fma_f32 v[36:37], v[140:141], v[2:3], v[40:41] op_sel_hi:[1,0,1]
	v_pk_fma_f32 v[38:39], v[142:143], v[2:3], v[42:43] op_sel_hi:[1,0,1]
	v_mul_f32_e32 v44, v36, v160
	v_mul_f32_e32 v50, v152, v36
	v_fmac_f32_e32 v44, v37, v161
	v_fmac_f32_e32 v50, v37, v153
	v_fmac_f32_e32 v44, v38, v162
	v_fmac_f32_e32 v50, v38, v154
	v_fmac_f32_e32 v44, v39, v163
	v_fmac_f32_e32 v50, v39, v155
	v_pk_mul_f32 v[40:41], v[172:173], v[158:159] op_sel_hi:[1,0]
	v_pk_mul_f32 v[42:43], v[174:175], v[158:159] op_sel_hi:[1,0]
	v_add_f32_dpp v2, v44, v44 quad_perm:[1,0,3,2] row_mask:0xf bank_mask:0xf bound_ctrl:1
	v_pk_fma_f32 v[40:41], v[36:37], v[168:169], v[40:41]
	v_pk_fma_f32 v[42:43], v[38:39], v[170:171], v[42:43]
	v_add_f32_dpp v2, v2, v2 quad_perm:[2,3,0,1] row_mask:0xf bank_mask:0xf bound_ctrl:1
	v_add_f32_e32 v228, v218, v219
	v_pk_fma_f32 v[34:35], v[26:27], v[34:35], 1.0 op_sel_hi:[1,1,0]
	ds_read_b128 v[136:139], v124 offset:25344
	ds_read_b128 v[140:143], v124 offset:25600
	ds_read_b128 v[144:147], v124 offset:25856
	v_add_f32_dpp v2, v2, v2 row_ror:4 row_mask:0xf bank_mask:0xf bound_ctrl:1
	ds_read_b128 v[148:151], v124 offset:26112
	ds_read_b128 v[152:155], v124 offset:26368
	ds_read_b32 v156, v110 offset:26624
	v_add_f32_dpp v2, v2, v2 row_ror:8 row_mask:0xf bank_mask:0xf bound_ctrl:1
	v_cndmask_b32_e64 v56, v47, v50, s[8:9]
	v_cndmask_b32_e64 v57, v50, v47, s[8:9]
	v_mov_b32_e32 v218, 0
	v_pk_mul_f32 v[34:35], v[216:217], v[34:35]
	v_add_f32_dpp v52, v57, v56 quad_perm:[1,0,3,2] row_mask:0xf bank_mask:0xf bound_ctrl:1
	v_cndmask_b32_e64 v56, v49, v52, s[10:11]
	v_cndmask_b32_e64 v57, v52, v49, s[10:11]
	s_nop 0
	s_nop 0
	v_add_f32_dpp v53, v57, v56 quad_perm:[2,3,0,1] row_mask:0xf bank_mask:0xf bound_ctrl:1
	v_cndmask_b32_e64 v56, v45, v53, s[12:13]
	v_cndmask_b32_e64 v57, v53, v45, s[12:13]
	s_nop 0
	s_nop 0
	v_add_f32_dpp v55, v57, v56 row_shl:4 row_mask:0xf bank_mask:0x5
	s_nop 0
	s_nop 0
	v_add_f32_dpp v55, v57, v56 row_shr:4 row_mask:0xf bank_mask:0xa
	v_cndmask_b32_e64 v56, v61, v55, s[14:15]
	v_cndmask_b32_e64 v57, v55, v61, s[14:15]
	s_nop 0
	s_nop 0
	v_add_f32_dpp v58, v57, v56 row_ror:8 row_mask:0xf bank_mask:0xf bound_ctrl:1
	ds_write_b32 v122, v58
	s_waitcnt lgkmcnt(7)
	v_pk_fma_f32 v[36:37], v[164:165], v[2:3], v[40:41] op_sel_hi:[1,0,1]
	v_pk_fma_f32 v[38:39], v[166:167], v[2:3], v[42:43] op_sel_hi:[1,0,1]
	v_mul_f32_e32 v44, v36, v188
	v_mul_f32_e32 v54, v176, v36
	v_fmac_f32_e32 v44, v37, v189
	v_fmac_f32_e32 v54, v37, v177
	v_fmac_f32_e32 v44, v38, v190
	v_fmac_f32_e32 v54, v38, v178
	v_fmac_f32_e32 v44, v39, v191
	v_fmac_f32_e32 v54, v39, v179
	v_pk_mul_f32 v[40:41], v[200:201], v[208:209] op_sel_hi:[1,0]
	v_pk_mul_f32 v[42:43], v[202:203], v[208:209] op_sel_hi:[1,0]
	v_add_f32_dpp v2, v44, v44 quad_perm:[1,0,3,2] row_mask:0xf bank_mask:0xf bound_ctrl:1
	v_pk_fma_f32 v[40:41], v[36:37], v[196:197], v[40:41]
	v_pk_fma_f32 v[42:43], v[38:39], v[198:199], v[42:43]
	v_add_f32_dpp v2, v2, v2 quad_perm:[2,3,0,1] row_mask:0xf bank_mask:0xf bound_ctrl:1
	v_pk_mul_f32 v[216:217], v[14:15], v[216:217]
	v_pk_mul_f32 v[220:221], v[30:31], v[34:35]
	ds_read_b128 v[160:163], v124 offset:26752
	ds_read_b128 v[164:167], v124 offset:27008
	ds_read_b128 v[168:171], v124 offset:27264
	v_add_f32_dpp v2, v2, v2 row_ror:4 row_mask:0xf bank_mask:0xf bound_ctrl:1
	ds_read_b128 v[172:175], v124 offset:27520
	ds_read_b128 v[176:179], v124 offset:27776
	ds_read_b32 v158, v110 offset:28032
	v_add_f32_dpp v2, v2, v2 row_ror:8 row_mask:0xf bank_mask:0xf bound_ctrl:1
	v_pk_mul_f32 v[222:223], v[216:217], v[216:217]
	v_fmac_f32_e32 v224, v6, v220
	s_waitcnt lgkmcnt(7)
	v_pk_fma_f32 v[36:37], v[192:193], v[2:3], v[40:41] op_sel_hi:[1,0,1]
	v_pk_fma_f32 v[38:39], v[194:195], v[2:3], v[42:43] op_sel_hi:[1,0,1]
	v_mul_f32_e32 v44, v36, v136
	v_mul_f32_e32 v59, v204, v36
	v_fmac_f32_e32 v44, v37, v137
	v_fmac_f32_e32 v59, v37, v205
	v_fmac_f32_e32 v44, v38, v138
	v_fmac_f32_e32 v59, v38, v206
	v_fmac_f32_e32 v44, v39, v139
	v_fmac_f32_e32 v59, v39, v207
	v_pk_mul_f32 v[40:41], v[148:149], v[156:157] op_sel_hi:[1,0]
	v_pk_mul_f32 v[42:43], v[150:151], v[156:157] op_sel_hi:[1,0]
	v_add_f32_dpp v2, v44, v44 quad_perm:[1,0,3,2] row_mask:0xf bank_mask:0xf bound_ctrl:1
	v_pk_fma_f32 v[40:41], v[36:37], v[144:145], v[40:41]
	v_pk_fma_f32 v[42:43], v[38:39], v[146:147], v[42:43]
	v_add_f32_dpp v2, v2, v2 quad_perm:[2,3,0,1] row_mask:0xf bank_mask:0xf bound_ctrl:1
	v_add_f32_e32 v228, v222, v228
	v_add_f32_e32 v228, v223, v228
	ds_read_b128 v[188:191], v124 offset:28160
	ds_read_b128 v[192:195], v124 offset:28416
	ds_read_b128 v[196:199], v124 offset:28672
	v_add_f32_dpp v2, v2, v2 row_ror:4 row_mask:0xf bank_mask:0xf bound_ctrl:1
	ds_read_b128 v[200:203], v124 offset:28928
	ds_read_b128 v[204:207], v124 offset:29184
	ds_read_b32 v208, v110 offset:29440
	v_add_f32_dpp v2, v2, v2 row_ror:8 row_mask:0xf bank_mask:0xf bound_ctrl:1
	v_cndmask_b32_e64 v56, v54, v59, s[8:9]
	v_cndmask_b32_e64 v57, v59, v54, s[8:9]
	v_fmac_f32_e32 v224, v7, v221
	v_mov_b32_e32 v220, 0
	s_waitcnt lgkmcnt(6)
; #define LAS __attribute__((address_space(3)))
; __device__ __forceinline__ float row16_sum(float x) { x += dpp_mov<0xB1>(x); x += dpp_mov<0x4E>(x); x += dpp_mov<0x124>(x); x += dpp_mov<0x128>(x); return x; }
; __device__ __forceinline__ void scan_stage(const u32x2 (&pz)[8], LAS float* buf, float* RKB, size_t mrow0, int t0, int tid, int h, int half, ...
;     ...
;     n2 = row16_sum(n2); rkb = row16_sum(rkb);
;     const float inv = __builtin_amdgcn_rsqf(fmaxf(n2, 1e-24f));
; __device__ __forceinline__ void scan_phase(const KAS Args& a, LAS unsigned char* lds, int i, const int tid_, const int bid, const int nblk) {
;     ...
;                 for (int t = 0; t < TC; ++t) {
;                     f32x4 kk4n = kk4, nb4n = nb4, w4n = w4, k4n = k4, r4n = r4; float vn = v;
;                     if (t + 1 < TC) { const LAS float* sn = sb + (t + 1) * SST;
;                         kk4n = *(const LAS f32x4*)(sn); nb4n = *(const LAS f32x4*)(sn + 64); w4n = *(const LAS f32x4*)(sn + 128); k4n = *(const LAS f32x4*)(sn + 192); r4n = *(const LAS f32x4*)(sn + 256); vn = vb[(t + 1) * SST]; }
;                     __builtin_amdgcn_sched_barrier(0x6);
;                     float sa = fmaf(S[3], kk4[3], fmaf(S[2], kk4[2], fmaf(S[1], kk4[1], S[0] * kk4[0])));
;                     const f32x4 Tm = S * w4 + k4 * v;
;                     sa = row16_sum(sa);
;                     S = Tm + nb4 * sa;
;                     float y = fmaf(S[3], r4[3], fmaf(S[2], r4[2], fmaf(S[1], r4[1], S[0] * r4[0]))); y = row16_sum(y);
;                     ysel = (cgp == (t & 15)) ? y : ysel;
;                     if ((t & 15) == 15) yb[(t - 15 + cgp) * 32 + rl] = ysel;
;                     kk4 = kk4n; nb4 = nb4n; w4 = w4n; k4 = k4n; r4 = r4n; v = vn; }
	v_pk_fma_f32 v[36:37], v[140:141], v[2:3], v[40:41] op_sel_hi:[1,0,1]
	v_pk_fma_f32 v[38:39], v[142:143], v[2:3], v[42:43] op_sel_hi:[1,0,1]
	v_add_f32_dpp v51, v57, v56 quad_perm:[1,0,3,2] row_mask:0xf bank_mask:0xf bound_ctrl:1
	v_mul_f32_e32 v44, v36, v160
	v_mul_f32_e32 v60, v152, v36
	v_fmac_f32_e32 v44, v37, v161
	v_fmac_f32_e32 v60, v37, v153
	v_fmac_f32_e32 v44, v38, v162
	v_fmac_f32_e32 v60, v38, v154
	v_fmac_f32_e32 v44, v39, v163
	v_fmac_f32_e32 v60, v39, v155
	v_pk_mul_f32 v[40:41], v[172:173], v[158:159] op_sel_hi:[1,0]
	v_pk_mul_f32 v[42:43], v[174:175], v[158:159] op_sel_hi:[1,0]
	v_add_f32_dpp v2, v44, v44 quad_perm:[1,0,3,2] row_mask:0xf bank_mask:0xf bound_ctrl:1
	v_pk_fma_f32 v[40:41], v[36:37], v[168:169], v[40:41]
	v_pk_fma_f32 v[42:43], v[38:39], v[170:171], v[42:43]
	v_add_f32_dpp v2, v2, v2 quad_perm:[2,3,0,1] row_mask:0xf bank_mask:0xf bound_ctrl:1
	v_add_f32_dpp v228, v228, v228 quad_perm:[1,0,3,2] row_mask:0xf bank_mask:0xf bound_ctrl:1
	v_add_f32_dpp v219, v224, v224 quad_perm:[1,0,3,2] row_mask:0xf bank_mask:0xf bound_ctrl:1
	ds_read_b128 v[136:139], v124 offset:29568
	ds_read_b128 v[140:143], v124 offset:29824
	ds_read_b128 v[144:147], v124 offset:30080
	v_add_f32_dpp v2, v2, v2 row_ror:4 row_mask:0xf bank_mask:0xf bound_ctrl:1
	ds_read_b128 v[148:151], v124 offset:30336
	ds_read_b128 v[152:155], v124 offset:30592
	ds_read_b32 v156, v110 offset:30848
	v_add_f32_dpp v2, v2, v2 row_ror:8 row_mask:0xf bank_mask:0xf bound_ctrl:1
	v_add_f32_dpp v228, v228, v228 quad_perm:[2,3,0,1] row_mask:0xf bank_mask:0xf bound_ctrl:1
	v_add_f32_dpp v219, v219, v219 quad_perm:[2,3,0,1] row_mask:0xf bank_mask:0xf bound_ctrl:1
	s_waitcnt lgkmcnt(6)
	v_pk_fma_f32 v[36:37], v[164:165], v[2:3], v[40:41] op_sel_hi:[1,0,1]
	v_pk_fma_f32 v[38:39], v[166:167], v[2:3], v[42:43] op_sel_hi:[1,0,1]
	v_mul_f32_e32 v44, v36, v188
	v_mul_f32_e32 v62, v176, v36
	v_fmac_f32_e32 v44, v37, v189
	v_fmac_f32_e32 v62, v37, v177
	v_fmac_f32_e32 v44, v38, v190
	v_fmac_f32_e32 v62, v38, v178
	v_fmac_f32_e32 v44, v39, v191
	v_fmac_f32_e32 v62, v39, v179
	v_pk_mul_f32 v[40:41], v[200:201], v[208:209] op_sel_hi:[1,0]
	v_pk_mul_f32 v[42:43], v[202:203], v[208:209] op_sel_hi:[1,0]
	v_add_f32_dpp v2, v44, v44 quad_perm:[1,0,3,2] row_mask:0xf bank_mask:0xf bound_ctrl:1
	v_pk_fma_f32 v[40:41], v[36:37], v[196:197], v[40:41]
	v_pk_fma_f32 v[42:43], v[38:39], v[198:199], v[42:43]
	v_add_f32_dpp v2, v2, v2 quad_perm:[2,3,0,1] row_mask:0xf bank_mask:0xf bound_ctrl:1
	v_add_f32_dpp v228, v228, v228 row_ror:4 row_mask:0xf bank_mask:0xf bound_ctrl:1
	v_add_f32_dpp v219, v219, v219 row_ror:4 row_mask:0xf bank_mask:0xf bound_ctrl:1
	ds_read_b128 v[160:163], v124 offset:30976
	ds_read_b128 v[164:167], v124 offset:31232
	ds_read_b128 v[168:171], v124 offset:31488
	v_add_f32_dpp v2, v2, v2 row_ror:4 row_mask:0xf bank_mask:0xf bound_ctrl:1
	ds_read_b128 v[172:175], v124 offset:31744
	ds_read_b128 v[176:179], v124 offset:32000
	ds_read_b32 v158, v110 offset:32256
	v_add_f32_dpp v2, v2, v2 row_ror:8 row_mask:0xf bank_mask:0xf bound_ctrl:1
	v_cndmask_b32_e64 v56, v60, v62, s[8:9]
	v_cndmask_b32_e64 v57, v62, v60, s[8:9]
	v_mov_b32_dpp v218, v228 row_ror:8 row_mask:0xf bank_mask:0xf
	v_mov_b32_dpp v220, v219 row_ror:8 row_mask:0xf bank_mask:0xf
	s_waitcnt lgkmcnt(6)
	v_pk_fma_f32 v[36:37], v[192:193], v[2:3], v[40:41] op_sel_hi:[1,0,1]
	v_pk_fma_f32 v[38:39], v[194:195], v[2:3], v[42:43] op_sel_hi:[1,0,1]
	v_add_f32_dpp v63, v57, v56 quad_perm:[1,0,3,2] row_mask:0xf bank_mask:0xf bound_ctrl:1
	v_cndmask_b32_e64 v56, v51, v63, s[10:11]
	v_cndmask_b32_e64 v57, v63, v51, s[10:11]
	v_mul_f32_e32 v44, v36, v136
	v_mul_f32_e32 v66, v204, v36
	v_add_f32_dpp v65, v57, v56 quad_perm:[2,3,0,1] row_mask:0xf bank_mask:0xf bound_ctrl:1
	v_fmac_f32_e32 v44, v37, v137
	v_fmac_f32_e32 v66, v37, v205
	v_fmac_f32_e32 v44, v38, v138
	v_fmac_f32_e32 v66, v38, v206
	v_fmac_f32_e32 v44, v39, v139
	v_fmac_f32_e32 v66, v39, v207
	v_pk_mul_f32 v[40:41], v[148:149], v[156:157] op_sel_hi:[1,0]
	v_pk_mul_f32 v[42:43], v[150:151], v[156:157] op_sel_hi:[1,0]
	v_add_f32_dpp v2, v44, v44 quad_perm:[1,0,3,2] row_mask:0xf bank_mask:0xf bound_ctrl:1
	v_pk_fma_f32 v[40:41], v[36:37], v[144:145], v[40:41]
	v_pk_fma_f32 v[42:43], v[38:39], v[146:147], v[42:43]
	v_add_f32_dpp v2, v2, v2 quad_perm:[2,3,0,1] row_mask:0xf bank_mask:0xf bound_ctrl:1
	v_add_f32_e32 v245, v219, v220
	v_add_f32_e32 v228, v228, v218
	ds_read_b128 v[188:191], v124 offset:32384
	ds_read_b128 v[192:195], v124 offset:32640
	ds_read_b128 v[196:199], v124 offset:32896
	v_add_f32_dpp v2, v2, v2 row_ror:4 row_mask:0xf bank_mask:0xf bound_ctrl:1
	ds_read_b128 v[200:203], v124 offset:33152
	ds_read_b128 v[204:207], v124 offset:33408
	ds_read_b32 v208, v110 offset:33664
	v_add_f32_dpp v2, v2, v2 row_ror:8 row_mask:0xf bank_mask:0xf bound_ctrl:1
	v_max_f32_e32 v228, 0x179abe15, v228
	v_lshlrev_b32_e32 v219, 16, v92
	s_waitcnt lgkmcnt(6)
; #define LAS __attribute__((address_space(3)))
; __device__ __forceinline__ float row16_sum(float x) { x += dpp_mov<0xB1>(x); x += dpp_mov<0x4E>(x); x += dpp_mov<0x124>(x); x += dpp_mov<0x128>(x); return x; }
; __device__ __forceinline__ void scan_stage(const u32x2 (&pz)[8], LAS float* buf, float* RKB, size_t mrow0, int t0, int tid, int h, int half, ...
;     ...
;         kkv[e] = k * kkc[e]; n2 += kkv[e] * kkv[e]; k2[e] = k * (1.0f + (ic[e] - 1.0f) * kac[e]); w[e] = __builtin_amdgcn_exp2f(-1.4426950408889634f * ew[e]); rkb += r[e] * k2[e] * rkc[e]; }
;     n2 = row16_sum(n2); rkb = row16_sum(rkb);
;     const float inv = __builtin_amdgcn_rsqf(fmaxf(n2, 1e-24f));
;     const f32x4 kkn = kkv * inv; f32x4 nb;
; __device__ __forceinline__ void scan_phase(const KAS Args& a, LAS unsigned char* lds, int i, const int tid_, const int bid, const int nblk) {
;     ...
;                 for (int t = 0; t < TC; ++t) {
;                     f32x4 kk4n = kk4, nb4n = nb4, w4n = w4, k4n = k4, r4n = r4; float vn = v;
;                     if (t + 1 < TC) { const LAS float* sn = sb + (t + 1) * SST;
;                         kk4n = *(const LAS f32x4*)(sn); nb4n = *(const LAS f32x4*)(sn + 64); w4n = *(const LAS f32x4*)(sn + 128); k4n = *(const LAS f32x4*)(sn + 192); r4n = *(const LAS f32x4*)(sn + 256); vn = vb[(t + 1) * SST]; }
;                     __builtin_amdgcn_sched_barrier(0x6);
;                     float sa = fmaf(S[3], kk4[3], fmaf(S[2], kk4[2], fmaf(S[1], kk4[1], S[0] * kk4[0])));
;                     const f32x4 Tm = S * w4 + k4 * v;
;                     sa = row16_sum(sa);
;                     S = Tm + nb4 * sa;
;                     float y = fmaf(S[3], r4[3], fmaf(S[2], r4[2], fmaf(S[1], r4[1], S[0] * r4[0]))); y = row16_sum(y);
;                     ysel = (cgp == (t & 15)) ? y : ysel;
;                     if ((t & 15) == 15) yb[(t - 15 + cgp) * 32 + rl] = ysel;
;                     kk4 = kk4n; nb4 = nb4n; w4 = w4n; k4 = k4n; r4 = r4n; v = vn; }
	v_pk_fma_f32 v[36:37], v[140:141], v[2:3], v[40:41] op_sel_hi:[1,0,1]
	v_pk_fma_f32 v[38:39], v[142:143], v[2:3], v[42:43] op_sel_hi:[1,0,1]
	v_mul_f32_e32 v44, v36, v160
	v_mul_f32_e32 v64, v152, v36
	v_fmac_f32_e32 v44, v37, v161
	v_fmac_f32_e32 v64, v37, v153
	v_fmac_f32_e32 v44, v38, v162
	v_fmac_f32_e32 v64, v38, v154
	v_fmac_f32_e32 v44, v39, v163
	v_fmac_f32_e32 v64, v39, v155
	v_pk_mul_f32 v[40:41], v[172:173], v[158:159] op_sel_hi:[1,0]
	v_pk_mul_f32 v[42:43], v[174:175], v[158:159] op_sel_hi:[1,0]
	v_add_f32_dpp v2, v44, v44 quad_perm:[1,0,3,2] row_mask:0xf bank_mask:0xf bound_ctrl:1
	v_pk_fma_f32 v[40:41], v[36:37], v[168:169], v[40:41]
	v_pk_fma_f32 v[42:43], v[38:39], v[170:171], v[42:43]
	v_add_f32_dpp v2, v2, v2 quad_perm:[2,3,0,1] row_mask:0xf bank_mask:0xf bound_ctrl:1
	v_rsq_f32_e32 v228, v228
	v_and_b32_e32 v221, 0xffff0000, v92
	ds_read_b128 v[136:139], v124 offset:33792
	ds_read_b128 v[140:143], v124 offset:34048
	ds_read_b128 v[144:147], v124 offset:34304
	v_add_f32_dpp v2, v2, v2 row_ror:4 row_mask:0xf bank_mask:0xf bound_ctrl:1
	ds_read_b128 v[148:151], v124 offset:34560
	ds_read_b128 v[152:155], v124 offset:34816
	ds_read_b32 v156, v110 offset:35072
	v_add_f32_dpp v2, v2, v2 row_ror:8 row_mask:0xf bank_mask:0xf bound_ctrl:1
	v_cndmask_b32_e64 v56, v66, v64, s[8:9]
	v_cndmask_b32_e64 v57, v64, v66, s[8:9]
	v_mul_f32_e32 v219, 0xbfb8aa3b, v219
	s_bitcmp1_b32 s62, 0
	s_cselect_b32 s2, 0xb000, 0
	s_waitcnt lgkmcnt(6)
	v_pk_fma_f32 v[36:37], v[164:165], v[2:3], v[40:41] op_sel_hi:[1,0,1]
	v_pk_fma_f32 v[38:39], v[166:167], v[2:3], v[42:43] op_sel_hi:[1,0,1]
	v_add_f32_dpp v67, v57, v56 quad_perm:[1,0,3,2] row_mask:0xf bank_mask:0xf bound_ctrl:1
	v_mul_f32_e32 v44, v36, v188
	v_mul_f32_e32 v46, v176, v36
	v_fmac_f32_e32 v44, v37, v189
	v_fmac_f32_e32 v46, v37, v177
	v_fmac_f32_e32 v44, v38, v190
	v_fmac_f32_e32 v46, v38, v178
	v_fmac_f32_e32 v44, v39, v191
	v_fmac_f32_e32 v46, v39, v179
	v_pk_mul_f32 v[40:41], v[200:201], v[208:209] op_sel_hi:[1,0]
	v_pk_mul_f32 v[42:43], v[202:203], v[208:209] op_sel_hi:[1,0]
	v_add_f32_dpp v2, v44, v44 quad_perm:[1,0,3,2] row_mask:0xf bank_mask:0xf bound_ctrl:1
	v_pk_fma_f32 v[40:41], v[36:37], v[196:197], v[40:41]
	v_pk_fma_f32 v[42:43], v[38:39], v[198:199], v[42:43]
	v_add_f32_dpp v2, v2, v2 quad_perm:[2,3,0,1] row_mask:0xf bank_mask:0xf bound_ctrl:1
	v_lshlrev_b32_e32 v222, 16, v93
	v_and_b32_e32 v223, 0xffff0000, v93
	ds_read_b128 v[160:163], v124 offset:35200
	ds_read_b128 v[164:167], v124 offset:35456
	ds_read_b128 v[168:171], v124 offset:35712
	v_add_f32_dpp v2, v2, v2 row_ror:4 row_mask:0xf bank_mask:0xf bound_ctrl:1
	ds_read_b128 v[172:175], v124 offset:35968
	ds_read_b128 v[176:179], v124 offset:36224
	ds_read_b32 v158, v110 offset:36480
	v_add_f32_dpp v2, v2, v2 row_ror:8 row_mask:0xf bank_mask:0xf bound_ctrl:1
	v_exp_f32_e32 v220, v219
	v_mul_f32_e32 v219, 0xbfb8aa3b, v221
	s_waitcnt lgkmcnt(6)
	v_pk_fma_f32 v[36:37], v[192:193], v[2:3], v[40:41] op_sel_hi:[1,0,1]
	v_pk_fma_f32 v[38:39], v[194:195], v[2:3], v[42:43] op_sel_hi:[1,0,1]
	v_mul_f32_e32 v44, v36, v136
	v_mul_f32_e32 v48, v204, v36
	v_fmac_f32_e32 v44, v37, v137
	v_fmac_f32_e32 v48, v37, v205
	v_fmac_f32_e32 v44, v38, v138
	v_fmac_f32_e32 v48, v38, v206
	v_fmac_f32_e32 v44, v39, v139
	v_fmac_f32_e32 v48, v39, v207
	v_pk_mul_f32 v[40:41], v[148:149], v[156:157] op_sel_hi:[1,0]
	v_pk_mul_f32 v[42:43], v[150:151], v[156:157] op_sel_hi:[1,0]
	v_add_f32_dpp v2, v44, v44 quad_perm:[1,0,3,2] row_mask:0xf bank_mask:0xf bound_ctrl:1
	v_pk_fma_f32 v[40:41], v[36:37], v[144:145], v[40:41]
	v_pk_fma_f32 v[42:43], v[38:39], v[146:147], v[42:43]
	v_add_f32_dpp v2, v2, v2 quad_perm:[2,3,0,1] row_mask:0xf bank_mask:0xf bound_ctrl:1
	v_exp_f32_e32 v221, v219
	v_mul_f32_e32 v219, 0xbfb8aa3b, v222
	ds_read_b128 v[188:191], v124 offset:36608
	ds_read_b128 v[192:195], v124 offset:36864
	ds_read_b128 v[196:199], v124 offset:37120
	v_add_f32_dpp v2, v2, v2 row_ror:4 row_mask:0xf bank_mask:0xf bound_ctrl:1
	ds_read_b128 v[200:203], v124 offset:37376
	ds_read_b128 v[204:207], v124 offset:37632
	ds_read_b32 v208, v110 offset:37888
	v_add_f32_dpp v2, v2, v2 row_ror:8 row_mask:0xf bank_mask:0xf bound_ctrl:1
	v_cndmask_b32_e64 v56, v46, v48, s[8:9]
	v_cndmask_b32_e64 v57, v48, v46, s[8:9]
	v_mul_f32_e32 v218, 0xbfb8aa3b, v223
	v_exp_f32_e32 v222, v219
	s_waitcnt lgkmcnt(6)
	v_pk_fma_f32 v[36:37], v[140:141], v[2:3], v[40:41] op_sel_hi:[1,0,1]
	v_pk_fma_f32 v[38:39], v[142:143], v[2:3], v[42:43] op_sel_hi:[1,0,1]
	v_add_f32_dpp v47, v57, v56 quad_perm:[1,0,3,2] row_mask:0xf bank_mask:0xf bound_ctrl:1
	v_cndmask_b32_e64 v56, v67, v47, s[10:11]
	v_cndmask_b32_e64 v57, v47, v67, s[10:11]
	v_mul_f32_e32 v44, v36, v160
	v_mul_f32_e32 v52, v152, v36
	v_add_f32_dpp v50, v57, v56 quad_perm:[2,3,0,1] row_mask:0xf bank_mask:0xf bound_ctrl:1
	v_fmac_f32_e32 v44, v37, v161
	v_fmac_f32_e32 v52, v37, v153
	v_cndmask_b32_e64 v56, v65, v50, s[12:13]
	v_fmac_f32_e32 v44, v38, v162
	v_fmac_f32_e32 v52, v38, v154
	v_cndmask_b32_e64 v57, v50, v65, s[12:13]
	v_fmac_f32_e32 v44, v39, v163
	v_fmac_f32_e32 v52, v39, v155
	v_pk_mul_f32 v[40:41], v[172:173], v[158:159] op_sel_hi:[1,0]
	v_pk_mul_f32 v[42:43], v[174:175], v[158:159] op_sel_hi:[1,0]
	v_add_f32_dpp v2, v44, v44 quad_perm:[1,0,3,2] row_mask:0xf bank_mask:0xf bound_ctrl:1
	v_pk_fma_f32 v[40:41], v[36:37], v[168:169], v[40:41]
	v_pk_fma_f32 v[42:43], v[38:39], v[170:171], v[42:43]
	v_add_f32_dpp v2, v2, v2 quad_perm:[2,3,0,1] row_mask:0xf bank_mask:0xf bound_ctrl:1
	v_exp_f32_e32 v223, v218
	v_pk_mul_f32 v[224:225], v[212:213], v[228:229] op_sel_hi:[1,0]
	ds_read_b128 v[136:139], v124 offset:38016
	ds_read_b128 v[140:143], v124 offset:38272
	ds_read_b128 v[144:147], v124 offset:38528
	v_add_f32_dpp v2, v2, v2 row_ror:4 row_mask:0xf bank_mask:0xf bound_ctrl:1
	ds_read_b128 v[148:151], v124 offset:38784
	ds_read_b128 v[152:155], v124 offset:39040
	ds_read_b32 v156, v110 offset:39296
	v_add_f32_dpp v2, v2, v2 row_ror:8 row_mask:0xf bank_mask:0xf bound_ctrl:1
	v_add_f32_dpp v49, v57, v56 row_shl:4 row_mask:0xf bank_mask:0x5
	v_pk_mul_f32 v[226:227], v[216:217], v[228:229] op_sel_hi:[1,0]
	v_add_u32_e32 v228, s2, v113
	s_waitcnt lgkmcnt(6)
; #define LAS __attribute__((address_space(3)))
; __device__ __forceinline__ float row16_sum(float x) { x += dpp_mov<0xB1>(x); x += dpp_mov<0x4E>(x); x += dpp_mov<0x124>(x); x += dpp_mov<0x128>(x); return x; }
; __device__ __forceinline__ void scan_stage(const u32x2 (&pz)[8], LAS float* buf, float* RKB, size_t mrow0, int t0, int tid, int h, int half, ...
;     ...
;     const f32x4 kkn = kkv * inv; f32x4 nb;
; #pragma unroll
;     for (int e = 0; e < 4; ++e) nb[e] = -kkn[e] * ic[e];
;     if (half == 0 && cgp == 0) RKB[(mrow0 + t0 + tl) * 8 + h] = rkb;
;     LAS float* sb = buf + tl * SST + 4 * cgp;
;     *(LAS f32x4*)(sb) = kkn; *(LAS f32x4*)(sb + 64) = nb; *(LAS f32x4*)(sb + 128) = w; *(LAS f32x4*)(sb + 192) = k2; *(LAS f32x4*)(sb + 256) = r;
; __device__ __forceinline__ void scan_phase(const KAS Args& a, LAS unsigned char* lds, int i, const int tid_, const int bid, const int nblk) {
;     ...
;                 for (int t = 0; t < TC; ++t) {
;                     f32x4 kk4n = kk4, nb4n = nb4, w4n = w4, k4n = k4, r4n = r4; float vn = v;
;                     if (t + 1 < TC) { const LAS float* sn = sb + (t + 1) * SST;
;                         kk4n = *(const LAS f32x4*)(sn); nb4n = *(const LAS f32x4*)(sn + 64); w4n = *(const LAS f32x4*)(sn + 128); k4n = *(const LAS f32x4*)(sn + 192); r4n = *(const LAS f32x4*)(sn + 256); vn = vb[(t + 1) * SST]; }
;                     __builtin_amdgcn_sched_barrier(0x6);
;                     float sa = fmaf(S[3], kk4[3], fmaf(S[2], kk4[2], fmaf(S[1], kk4[1], S[0] * kk4[0])));
;                     const f32x4 Tm = S * w4 + k4 * v;
;                     sa = row16_sum(sa);
;                     S = Tm + nb4 * sa;
;                     float y = fmaf(S[3], r4[3], fmaf(S[2], r4[2], fmaf(S[1], r4[1], S[0] * r4[0]))); y = row16_sum(y);
;                     ysel = (cgp == (t & 15)) ? y : ysel;
;                     if ((t & 15) == 15) yb[(t - 15 + cgp) * 32 + rl] = ysel;
;                     kk4 = kk4n; nb4 = nb4n; w4 = w4n; k4 = k4n; r4 = r4n; v = vn; }
	v_pk_fma_f32 v[36:37], v[164:165], v[2:3], v[40:41] op_sel_hi:[1,0,1]
	v_pk_fma_f32 v[38:39], v[166:167], v[2:3], v[42:43] op_sel_hi:[1,0,1]
	v_add_f32_dpp v49, v57, v56 row_shr:4 row_mask:0xf bank_mask:0xa
	v_mul_f32_e32 v44, v36, v188
	v_mul_f32_e32 v45, v176, v36
	v_fmac_f32_e32 v44, v37, v189
	v_fmac_f32_e32 v45, v37, v177
	v_fmac_f32_e32 v44, v38, v190
	v_fmac_f32_e32 v45, v38, v178
	v_fmac_f32_e32 v44, v39, v191
	v_fmac_f32_e32 v45, v39, v179
	v_pk_mul_f32 v[40:41], v[200:201], v[208:209] op_sel_hi:[1,0]
	v_pk_mul_f32 v[42:43], v[202:203], v[208:209] op_sel_hi:[1,0]
	v_add_f32_dpp v2, v44, v44 quad_perm:[1,0,3,2] row_mask:0xf bank_mask:0xf bound_ctrl:1
	v_pk_fma_f32 v[40:41], v[36:37], v[196:197], v[40:41]
	v_pk_fma_f32 v[42:43], v[38:39], v[198:199], v[42:43]
	v_add_f32_dpp v2, v2, v2 quad_perm:[2,3,0,1] row_mask:0xf bank_mask:0xf bound_ctrl:1
	v_pk_mul_f32 v[212:213], v[214:215], v[226:227] neg_lo:[0,1] neg_hi:[0,1]
	v_add_u32_e32 v214, v228, v114
	ds_read_b128 v[160:163], v124 offset:39424
	ds_read_b128 v[164:167], v124 offset:39680
	ds_read_b128 v[168:171], v124 offset:39936
	v_add_f32_dpp v2, v2, v2 row_ror:4 row_mask:0xf bank_mask:0xf bound_ctrl:1
	ds_read_b128 v[172:175], v124 offset:40192
	ds_read_b128 v[176:179], v124 offset:40448
	ds_read_b32 v158, v110 offset:40704
	v_add_f32_dpp v2, v2, v2 row_ror:8 row_mask:0xf bank_mask:0xf bound_ctrl:1
	v_cndmask_b32_e64 v56, v52, v45, s[8:9]
	v_cndmask_b32_e64 v57, v45, v52, s[8:9]
	v_pk_mul_f32 v[210:211], v[210:211], v[224:225] neg_lo:[0,1] neg_hi:[0,1]
	ds_write_b128 v214, v[224:227]
	s_waitcnt lgkmcnt(7)
	v_pk_fma_f32 v[36:37], v[192:193], v[2:3], v[40:41] op_sel_hi:[1,0,1]
	v_pk_fma_f32 v[38:39], v[194:195], v[2:3], v[42:43] op_sel_hi:[1,0,1]
	v_add_f32_dpp v53, v57, v56 quad_perm:[1,0,3,2] row_mask:0xf bank_mask:0xf bound_ctrl:1
	v_mul_f32_e32 v44, v36, v136
	v_mul_f32_e32 v61, v204, v36
	v_fmac_f32_e32 v44, v37, v137
	v_fmac_f32_e32 v61, v37, v205
	v_fmac_f32_e32 v44, v38, v138
	v_fmac_f32_e32 v61, v38, v206
	v_fmac_f32_e32 v44, v39, v139
	v_fmac_f32_e32 v61, v39, v207
	v_pk_mul_f32 v[40:41], v[148:149], v[156:157] op_sel_hi:[1,0]
	v_pk_mul_f32 v[42:43], v[150:151], v[156:157] op_sel_hi:[1,0]
	v_add_f32_dpp v2, v44, v44 quad_perm:[1,0,3,2] row_mask:0xf bank_mask:0xf bound_ctrl:1
	v_pk_fma_f32 v[40:41], v[36:37], v[144:145], v[40:41]
	v_pk_fma_f32 v[42:43], v[38:39], v[146:147], v[42:43]
	v_add_f32_dpp v2, v2, v2 quad_perm:[2,3,0,1] row_mask:0xf bank_mask:0xf bound_ctrl:1
	ds_write_b128 v214, v[210:213] offset:256
	ds_write_b128 v214, v[220:223] offset:512
	ds_read_b128 v[188:191], v124 offset:40832
	ds_read_b128 v[192:195], v124 offset:41088
	ds_read_b128 v[196:199], v124 offset:41344
	v_add_f32_dpp v2, v2, v2 row_ror:4 row_mask:0xf bank_mask:0xf bound_ctrl:1
	ds_read_b128 v[200:203], v124 offset:41600
	ds_read_b128 v[204:207], v124 offset:41856
	ds_read_b32 v208, v110 offset:42112
	v_add_f32_dpp v2, v2, v2 row_ror:8 row_mask:0xf bank_mask:0xf bound_ctrl:1
	ds_write_b128 v214, v[32:35] offset:768
	ds_write_b128 v214, v[28:31] offset:1024
	s_waitcnt lgkmcnt(11)
	v_pk_fma_f32 v[36:37], v[140:141], v[2:3], v[40:41] op_sel_hi:[1,0,1]
	v_pk_fma_f32 v[38:39], v[142:143], v[2:3], v[42:43] op_sel_hi:[1,0,1]
	v_mul_f32_e32 v44, v36, v160
	v_mul_f32_e32 v55, v152, v36
	v_fmac_f32_e32 v44, v37, v161
	v_fmac_f32_e32 v55, v37, v153
	v_fmac_f32_e32 v44, v38, v162
	v_fmac_f32_e32 v55, v38, v154
	v_fmac_f32_e32 v44, v39, v163
	v_fmac_f32_e32 v55, v39, v155
	v_pk_mul_f32 v[40:41], v[172:173], v[158:159] op_sel_hi:[1,0]
	v_pk_mul_f32 v[42:43], v[174:175], v[158:159] op_sel_hi:[1,0]
	v_add_f32_dpp v2, v44, v44 quad_perm:[1,0,3,2] row_mask:0xf bank_mask:0xf bound_ctrl:1
	v_pk_fma_f32 v[40:41], v[36:37], v[168:169], v[40:41]
	v_pk_fma_f32 v[42:43], v[38:39], v[170:171], v[42:43]
	v_add_f32_dpp v2, v2, v2 quad_perm:[2,3,0,1] row_mask:0xf bank_mask:0xf bound_ctrl:1
	ds_read_b128 v[136:139], v124 offset:42240
	ds_read_b128 v[140:143], v124 offset:42496
	ds_read_b128 v[144:147], v124 offset:42752
	v_add_f32_dpp v2, v2, v2 row_ror:4 row_mask:0xf bank_mask:0xf bound_ctrl:1
	ds_read_b128 v[148:151], v124 offset:43008
	ds_read_b128 v[152:155], v124 offset:43264
	ds_read_b32 v156, v110 offset:43520
	v_add_f32_dpp v2, v2, v2 row_ror:8 row_mask:0xf bank_mask:0xf bound_ctrl:1
	v_cndmask_b32_e64 v56, v61, v55, s[8:9]
	v_cndmask_b32_e64 v57, v55, v61, s[8:9]
	s_waitcnt lgkmcnt(8)
; #define LAS __attribute__((address_space(3)))
; __device__ __forceinline__ float row16_sum(float x) { x += dpp_mov<0xB1>(x); x += dpp_mov<0x4E>(x); x += dpp_mov<0x124>(x); x += dpp_mov<0x128>(x); return x; }
; __device__ __forceinline__ void scan_stage(const u32x2 (&pz)[8], LAS float* buf, float* RKB, size_t mrow0, int t0, int tid, int h, int half, ...
;     ...
;     if (half == 0 && cgp == 0) RKB[(mrow0 + t0 + tl) * 8 + h] = rkb;
; __device__ __forceinline__ void scan_phase(const KAS Args& a, LAS unsigned char* lds, int i, const int tid_, const int bid, const int nblk) {
;     ...
;                 for (int t = 0; t < TC; ++t) {
;                     f32x4 kk4n = kk4, nb4n = nb4, w4n = w4, k4n = k4, r4n = r4; float vn = v;
;                     if (t + 1 < TC) { const LAS float* sn = sb + (t + 1) * SST;
;                         kk4n = *(const LAS f32x4*)(sn); nb4n = *(const LAS f32x4*)(sn + 64); w4n = *(const LAS f32x4*)(sn + 128); k4n = *(const LAS f32x4*)(sn + 192); r4n = *(const LAS f32x4*)(sn + 256); vn = vb[(t + 1) * SST]; }
;                     __builtin_amdgcn_sched_barrier(0x6);
;                     float sa = fmaf(S[3], kk4[3], fmaf(S[2], kk4[2], fmaf(S[1], kk4[1], S[0] * kk4[0])));
;                     const f32x4 Tm = S * w4 + k4 * v;
;                     sa = row16_sum(sa);
;                     S = Tm + nb4 * sa;
;                     float y = fmaf(S[3], r4[3], fmaf(S[2], r4[2], fmaf(S[1], r4[1], S[0] * r4[0]))); y = row16_sum(y);
;                     ysel = (cgp == (t & 15)) ? y : ysel;
;                     if ((t & 15) == 15) yb[(t - 15 + cgp) * 32 + rl] = ysel;
;                     kk4 = kk4n; nb4 = nb4n; w4 = w4n; k4 = k4n; r4 = r4n; v = vn; }
	v_pk_fma_f32 v[36:37], v[164:165], v[2:3], v[40:41] op_sel_hi:[1,0,1]
	v_pk_fma_f32 v[38:39], v[166:167], v[2:3], v[42:43] op_sel_hi:[1,0,1]
	v_add_f32_dpp v58, v57, v56 quad_perm:[1,0,3,2] row_mask:0xf bank_mask:0xf bound_ctrl:1
	v_cndmask_b32_e64 v56, v53, v58, s[10:11]
	v_cndmask_b32_e64 v57, v58, v53, s[10:11]
	v_mul_f32_e32 v44, v36, v188
	v_mul_f32_e32 v59, v176, v36
	v_add_f32_dpp v54, v57, v56 quad_perm:[2,3,0,1] row_mask:0xf bank_mask:0xf bound_ctrl:1
	v_fmac_f32_e32 v44, v37, v189
	v_fmac_f32_e32 v59, v37, v177
	v_fmac_f32_e32 v44, v38, v190
	v_fmac_f32_e32 v59, v38, v178
	v_fmac_f32_e32 v44, v39, v191
	v_fmac_f32_e32 v59, v39, v179
	v_pk_mul_f32 v[40:41], v[200:201], v[208:209] op_sel_hi:[1,0]
	v_pk_mul_f32 v[42:43], v[202:203], v[208:209] op_sel_hi:[1,0]
	v_add_f32_dpp v2, v44, v44 quad_perm:[1,0,3,2] row_mask:0xf bank_mask:0xf bound_ctrl:1
	v_pk_fma_f32 v[40:41], v[36:37], v[196:197], v[40:41]
	v_pk_fma_f32 v[42:43], v[38:39], v[198:199], v[42:43]
	v_add_f32_dpp v2, v2, v2 quad_perm:[2,3,0,1] row_mask:0xf bank_mask:0xf bound_ctrl:1
	ds_read_b128 v[160:163], v124 offset:43648
	ds_read_b128 v[164:167], v124 offset:43904
	ds_read_b128 v[168:171], v124 offset:44160
	v_add_f32_dpp v2, v2, v2 row_ror:4 row_mask:0xf bank_mask:0xf bound_ctrl:1
	ds_read_b128 v[172:175], v124 offset:44416
	ds_read_b128 v[176:179], v124 offset:44672
	ds_read_b32 v158, v110 offset:44928
	v_add_f32_dpp v2, v2, v2 row_ror:8 row_mask:0xf bank_mask:0xf bound_ctrl:1
	s_waitcnt lgkmcnt(6)
	v_pk_fma_f32 v[36:37], v[192:193], v[2:3], v[40:41] op_sel_hi:[1,0,1]
	v_pk_fma_f32 v[38:39], v[194:195], v[2:3], v[42:43] op_sel_hi:[1,0,1]
	v_mul_f32_e32 v44, v36, v136
	v_mul_f32_e32 v60, v204, v36
	v_fmac_f32_e32 v44, v37, v137
	v_fmac_f32_e32 v60, v37, v205
	v_fmac_f32_e32 v44, v38, v138
	v_fmac_f32_e32 v60, v38, v206
	v_fmac_f32_e32 v44, v39, v139
	v_fmac_f32_e32 v60, v39, v207
	v_pk_mul_f32 v[40:41], v[148:149], v[156:157] op_sel_hi:[1,0]
	v_pk_mul_f32 v[42:43], v[150:151], v[156:157] op_sel_hi:[1,0]
	v_add_f32_dpp v2, v44, v44 quad_perm:[1,0,3,2] row_mask:0xf bank_mask:0xf bound_ctrl:1
	v_pk_fma_f32 v[40:41], v[36:37], v[144:145], v[40:41]
	v_pk_fma_f32 v[42:43], v[38:39], v[146:147], v[42:43]
	v_add_f32_dpp v2, v2, v2 quad_perm:[2,3,0,1] row_mask:0xf bank_mask:0xf bound_ctrl:1
	v_cndmask_b32_e64 v56, v59, v60, s[8:9]
	v_cndmask_b32_e64 v57, v60, v59, s[8:9]
	v_add_f32_dpp v2, v2, v2 row_ror:4 row_mask:0xf bank_mask:0xf bound_ctrl:1
	s_nop 0
	v_add_f32_dpp v62, v57, v56 quad_perm:[1,0,3,2] row_mask:0xf bank_mask:0xf bound_ctrl:1
	v_add_f32_dpp v2, v2, v2 row_ror:8 row_mask:0xf bank_mask:0xf bound_ctrl:1
	s_waitcnt lgkmcnt(0)
	v_pk_fma_f32 v[36:37], v[140:141], v[2:3], v[40:41] op_sel_hi:[1,0,1]
	v_pk_fma_f32 v[38:39], v[142:143], v[2:3], v[42:43] op_sel_hi:[1,0,1]
	v_mul_f32_e32 v44, v36, v160
	v_mul_f32_e32 v51, v152, v36
	v_fmac_f32_e32 v44, v37, v161
	v_fmac_f32_e32 v51, v37, v153
	v_fmac_f32_e32 v44, v38, v162
	v_fmac_f32_e32 v51, v38, v154
	v_fmac_f32_e32 v44, v39, v163
	v_fmac_f32_e32 v51, v39, v155
	v_pk_mul_f32 v[40:41], v[172:173], v[158:159] op_sel_hi:[1,0]
	v_pk_mul_f32 v[42:43], v[174:175], v[158:159] op_sel_hi:[1,0]
	v_add_f32_dpp v2, v44, v44 quad_perm:[1,0,3,2] row_mask:0xf bank_mask:0xf bound_ctrl:1
	v_pk_fma_f32 v[40:41], v[36:37], v[168:169], v[40:41]
	v_pk_fma_f32 v[42:43], v[38:39], v[170:171], v[42:43]
	v_add_f32_dpp v2, v2, v2 quad_perm:[2,3,0,1] row_mask:0xf bank_mask:0xf bound_ctrl:1
	s_nop 0
	s_nop 0
	v_add_f32_dpp v2, v2, v2 row_ror:4 row_mask:0xf bank_mask:0xf bound_ctrl:1
	s_nop 0
	s_nop 0
	v_add_f32_dpp v2, v2, v2 row_ror:8 row_mask:0xf bank_mask:0xf bound_ctrl:1
	v_pk_fma_f32 v[36:37], v[164:165], v[2:3], v[40:41] op_sel_hi:[1,0,1]
	v_pk_fma_f32 v[38:39], v[166:167], v[2:3], v[42:43] op_sel_hi:[1,0,1]
	v_mul_f32_e32 v63, v176, v36
	v_fmac_f32_e32 v63, v37, v177
	v_fmac_f32_e32 v63, v38, v178
	v_fmac_f32_e32 v63, v39, v179
	v_cndmask_b32_e64 v56, v51, v63, s[8:9]
	v_cndmask_b32_e64 v57, v63, v51, s[8:9]
	s_nop 0
	s_nop 0
	v_add_f32_dpp v66, v57, v56 quad_perm:[1,0,3,2] row_mask:0xf bank_mask:0xf bound_ctrl:1
	v_cndmask_b32_e64 v56, v62, v66, s[10:11]
	v_cndmask_b32_e64 v57, v66, v62, s[10:11]
	s_nop 0
	s_nop 0
	v_add_f32_dpp v64, v57, v56 quad_perm:[2,3,0,1] row_mask:0xf bank_mask:0xf bound_ctrl:1
	v_cndmask_b32_e64 v56, v54, v64, s[12:13]
	v_cndmask_b32_e64 v57, v64, v54, s[12:13]
	s_nop 0
	s_nop 0
	v_add_f32_dpp v46, v57, v56 row_shl:4 row_mask:0xf bank_mask:0x5
	s_nop 0
	s_nop 0
	v_add_f32_dpp v46, v57, v56 row_shr:4 row_mask:0xf bank_mask:0xa
	v_cndmask_b32_e64 v56, v49, v46, s[14:15]
	v_cndmask_b32_e64 v57, v46, v49, s[14:15]
	s_nop 0
	s_nop 0
	v_add_f32_dpp v48, v57, v56 row_ror:8 row_mask:0xf bank_mask:0xf bound_ctrl:1
	ds_write_b32 v122, v48 offset:2048
	s_cbranch_vccnz .LBB0_183
	s_and_saveexec_b64 s[2:3], s[42:43]
	s_cbranch_execz .Lsc_nost
	v_lshl_add_u64 v[52:53], s[88:89], 0, v[100:101]
	global_store_dword v[52:53], v245, off
